# v074 + next tile's near/cinit scalars evaluated in the PV/exp block (top keeps a flag move and one compare), last-tiles handling out of line, three exps per MFMA gap so the tail holds only the last co
# baseline (speedup 1.0000x reference)
; __device__ __forceinline__ int pi32(int r) { return (r & ~12) | ((r & 4) << 1) | ((r & 8) >> 1); }
; #define AT_DMA(tr) do { const unsigned sb_ = (unsigned)__builtin_amdgcn_readfirstlane(dk + (((tr) & (NSTG - 1)) * STAGE)); const size_t ko_ = (size_t)(tr) * 26 * 4096, vo_ = (size_t)(tr) * 640 * 64; \
;         glds16(kg + ko_, sb_ + OFF_K0); if (!WIN) glds16(kg + ko_ + 4096, sb_ + OFF_K1); glds16(vg + vo_, sb_ + OFF_V); if (!WIN) glds16(vg + vo_ + 64 * 64, sb_ + OFF_V + 8192); } while (0)
; template <bool WIN> ...
;     ...
;     const bf16_t* kg = QK + ((size_t)((seq_base >> 6) + t_lo) * 26 * 64 + drow) * 64 + dch * 8 + kcol0 * 64;
;     const bf16_t* vg = VT + ((size_t)((seq_base >> 6) + t_lo) * 640 + vrow0 + drow) * 64 + dch * 8;
;     const unsigned dk = ldsb + wid * 1024;
;     ...
;     constexpr int NPW = WIN ? 2 : 4;
;     bf16x8 qfr[4];
;     { const int qrow = seq_base + qw + l31; const bf16_t* qp = QK + ((size_t)((qrow >> 6) * 26 + (qcol >> 6)) * 64 + (qrow & 63)) * 64 + hi * 8;
; #pragma unroll
;       for (int ds = 0; ds < 4; ++ds) qfr[ds] = *(const bf16x8*)(qp + ds * 16); }
;     ...
;     AT_DMA(0); if (NT > 1) AT_DMA(1); if (NT > 2) AT_DMA(2);
;     constexpr float THR = 8.0f;
;     float m_ref = WIN ? sinkp[2 * hsel + half] * LOG2E : 0.f;
;     float l_run = (WIN && hi == 0) ? 1.f : 0.f;
;     float cbase = 0.f;
;     f32x16 cvec;
; #pragma unroll
;     for (int r = 0; r < 16; ++r) cvec[r] = cbase - m_ref;
;     f32x16 o[NDB];
; #pragma unroll
;     for (int db = 0; db < NDB; ++db)
; #pragma unroll
;         for (int r = 0; r < 16; ++r) o[db][r] = 0.f;
;     const int krow = pi32(l31), fK = (krow >> 1) & 7, fV = (l31 >> 1) & 7;
;     int kx[4], vx[4];
; #pragma unroll
;     for (int c = 0; c < 4; ++c) { kx[c] = (WIN ? OFF_K0 : (half ? OFF_K1 : OFF_K0)) + krow * 128 + (((2 * c + hi) ^ fK) << 4); vx[c] = OFF_V + l31 * 128 + (((2 * c + hi) ^ fV) << 4); }
;     const int qabs = qw + l31;
;     const float cfar_lo = __uint_as_float(__builtin_amdgcn_readfirstlane(__float_as_uint(lut[0]))), cfar_hi = __uint_as_float(__builtin_amdgcn_readfirstlane(__float_as_uint(lut[LUTW - 1])));
;     asm volatile("" : "+v"(qfr[0]), "+v"(qfr[1]), "+v"(qfr[2]), "+v"(qfr[3]));
.LBB0_244:
	s_lshl_b32 s62, s33, 5
	s_lshl_b32 s20, s33, 2
	s_and_b32 s62, s62, 32
	v_readfirstlane_b32 s64, v230
	s_and_b32 s20, s20, 24
	s_add_i32 s62, s62, s22
	s_bfe_u32 s77, s64, 0x20006
	s_or_b32 s20, s20, s24
	s_lshl_b32 s62, s62, 7
	s_lshl_b32 s82, s77, 5
	s_lshl_b32 s20, s20, 11
	s_or_b32 s78, s82, s62
	s_and_b32 s20, s20, 0xe000
	s_lshr_b32 s76, s64, 8
	v_or_b32_e32 v4, s78, v185
	v_add_u32_e32 v170, s20, v4
	s_add_i32 s62, s76, s66
	v_ashrrev_i32_e32 v2, 6, v170
	v_mov_b32_e32 v0, s62
	v_mad_u64_u32 v[2:3], s[62:63], v2, 26, v[0:1]
	v_ashrrev_i32_e32 v3, 31, v2
	v_lshlrev_b64 v[2:3], 13, v[2:3]
	v_lshlrev_b32_e32 v0, 7, v4
	v_lshl_add_u64 v[2:3], s[6:7], 0, v[2:3]
	v_and_b32_e32 v4, 0x1f80, v0
	v_mov_b32_e32 v5, v1
	v_lshl_add_u64 v[2:3], v[2:3], 0, v[4:5]
	v_lshl_add_u64 v[2:3], v[2:3], 0, v[164:165]
	global_load_dwordx4 v[114:117], v[2:3], off offset:96
	global_load_dwordx4 v[118:121], v[2:3], off offset:64
	global_load_dwordx4 v[122:125], v[2:3], off offset:32
	global_load_dwordx4 v[126:129], v[2:3], off
	s_lshl_b32 s62, s31, 11
	s_and_b32 s62, s62, 0xffffc000
	s_or_b32 s62, s26, s62
	v_cndmask_b32_e64 v0, 0, 1, s[38:39]
	s_lshr_b32 s81, s62, 13
	v_readfirstlane_b32 s62, v0
	s_lshr_b32 s63, s64, 4
	s_lshl_b32 s83, s62, 12
	s_lshr_b32 s62, s64, 6
	s_and_b32 s63, s63, 4
	s_lshl_b32 s84, s62, 3
	v_bitop3_b32 v4, s63, v186, v189 bitop3:0x36
	s_lshr_b32 s63, s20, 6
	v_or_b32_e32 v0, s84, v188
	s_mul_i32 s20, s63, 0x680
	v_lshl_add_u64 v[2:3], s[20:21], 0, v[0:1]
	v_lshlrev_b64 v[2:3], 7, v[2:3]
	v_lshl_add_u64 v[2:3], s[6:7], 0, v[2:3]
	v_lshlrev_b32_e32 v4, 4, v4
	v_lshl_add_u64 v[2:3], v[2:3], 0, v[4:5]
	s_mul_i32 s20, s63, 0x280
	v_add_u32_e32 v6, s12, v0
	v_mov_b32_e32 v7, v1
	v_lshl_add_u64 v[2:3], v[2:3], 0, s[18:19]
	v_lshl_add_u64 v[6:7], v[6:7], 0, s[20:21]
	s_lshl_b32 s20, s62, 10
	s_mov_b64 s[62:63], 0x24000
	v_lshl_add_u64 v[8:9], v[2:3], 0, s[62:63]
	s_add_i32 s20, s20, 0
	s_mov_b32 s62, m0
	s_mov_b32 m0, s20
	s_nop 0
	global_load_lds_dwordx4 v[8:9], off
	s_mov_b32 m0, s62
	s_mov_b64 s[62:63], 0x26000
	v_lshlrev_b64 v[6:7], 7, v[6:7]
	v_lshl_add_u64 v[8:9], v[2:3], 0, s[62:63]
	s_add_i32 s62, s20, 0x2000
	v_lshl_add_u64 v[6:7], s[4:5], 0, v[6:7]
	s_mov_b32 s63, m0
	s_mov_b32 m0, s62
	s_nop 0
	global_load_lds_dwordx4 v[8:9], off
	s_mov_b32 m0, s63
	s_add_i32 s62, s20, 0x4000
	v_lshl_add_u64 v[6:7], v[6:7], 0, v[4:5]
	s_mov_b32 s63, m0
	s_mov_b32 m0, s62
	s_nop 0
	global_load_lds_dwordx4 v[6:7], off
	s_mov_b32 m0, s63
	s_add_i32 s62, s20, 0x6000
	v_lshl_add_u64 v[8:9], v[6:7], 0, s[40:41]
	s_mov_b32 s63, m0
	s_mov_b32 m0, s62
	s_nop 0
	global_load_lds_dwordx4 v[8:9], off
	s_mov_b32 m0, s63
	s_add_i32 s62, s20, 0x8000
	v_lshl_add_u64 v[8:9], v[2:3], 0, s[42:43]
	s_mov_b32 s63, m0
	s_mov_b32 m0, s62
	s_nop 0
	global_load_lds_dwordx4 v[8:9], off
	s_mov_b32 m0, s63
	s_add_i32 s62, s20, 0xa000
	v_lshl_add_u64 v[8:9], v[2:3], 0, s[46:47]
	s_mov_b32 s63, m0
	s_mov_b32 m0, s62
	s_nop 0
	global_load_lds_dwordx4 v[8:9], off
	s_mov_b32 m0, s63
	s_add_i32 s62, s20, 0xc000
	v_lshl_add_u64 v[8:9], v[6:7], 0, s[48:49]
	s_mov_b32 s63, m0
	s_mov_b32 m0, s62
	s_nop 0
	global_load_lds_dwordx4 v[8:9], off
	s_mov_b32 m0, s63
	s_add_i32 s62, s20, 0xe000
	v_lshl_add_u64 v[8:9], v[6:7], 0, s[50:51]
	s_mov_b32 s63, m0
	s_mov_b32 m0, s62
	s_nop 0
	global_load_lds_dwordx4 v[8:9], off
	s_mov_b32 m0, s63
	s_add_i32 s62, s20, 0x10000
	v_lshl_add_u64 v[8:9], v[2:3], 0, s[52:53]
	s_mov_b32 s63, m0
	s_mov_b32 m0, s62
	s_nop 0
	global_load_lds_dwordx4 v[8:9], off
	s_mov_b32 m0, s63
	s_add_i32 s62, s20, 0x12000
	v_lshl_add_u64 v[2:3], v[2:3], 0, s[54:55]
	s_mov_b32 s63, m0
	s_mov_b32 m0, s62
	s_nop 0
	global_load_lds_dwordx4 v[2:3], off
	s_mov_b32 m0, s63
	s_add_i32 s62, s20, 0x14000
	v_lshl_add_u64 v[2:3], v[6:7], 0, s[56:57]
	s_add_i32 s62, s20, 0x16000
	v_lshl_add_u64 v[2:3], v[6:7], 0, s[58:59]
	s_cmpk_lt_u32 s64, 0x100
	s_cselect_b64 s[62:63], -1, 0
	s_and_b64 s[64:65], s[62:63], exec
	s_cselect_b32 s64, 0, 0x2000
	s_add_i32 s67, s27, 0x20000
	v_mov_b32_e32 v2, s67
	ds_read_b32 v3, v2 offset:14336
	ds_read_b32 v2, v2 offset:16124
	v_or_b32_e32 v162, s64, v177
	v_mov_b32_e32 v14, v1
	v_mov_b32_e32 v15, v1
	s_waitcnt lgkmcnt(1)
	v_readfirstlane_b32 s79, v3
	s_waitcnt lgkmcnt(0)
	v_readfirstlane_b32 s80, v2
	v_add_u32_e32 v2, s84, v197
	v_mov_b32_e32 v3, v1
	v_lshlrev_b64 v[2:3], 7, v[2:3]
	v_mad_u64_u32 v[2:3], s[64:65], s81, v199, v[2:3]
	v_or_b32_e32 v2, v2, v4
	v_lshl_add_u64 v[172:173], s[36:37], 0, v[2:3]
	v_lshlrev_b64 v[2:3], 7, v[0:1]
	v_mad_u64_u32 v[2:3], s[64:65], s81, v200, v[2:3]
	s_or_b32 s64, s82, s83
	v_or_b32_e32 v2, v2, v4
	v_add_lshl_u32 v0, s64, v198, 2
	v_lshl_add_u64 v[174:175], s[16:17], 0, v[2:3]
	v_sub_u32_e32 v171, v195, v0
	s_sub_i32 s64, s28, s82
	v_mov_b32_e32 v0, v1
	v_mov_b32_e32 v2, v1
	v_mov_b32_e32 v3, v1
	v_mov_b32_e32 v4, v1
	v_mov_b32_e32 v6, v1
	v_mov_b32_e32 v7, v1
	v_mov_b32_e32 v8, v1
	v_mov_b32_e32 v9, v1
	v_mov_b32_e32 v10, v1
	v_mov_b32_e32 v11, v1
	v_mov_b32_e32 v12, v1
	v_mov_b32_e32 v13, v1
	v_mov_b64_e32 v[64:65], v[14:15]
	v_mov_b64_e32 v[48:49], v[14:15]
	v_mov_b64_e32 v[32:33], v[14:15]
	s_sub_i32 s81, s64, s83
	s_add_i32 s64, s29, s83
	v_mov_b64_e32 v[62:63], v[12:13]
	v_mov_b64_e32 v[60:61], v[10:11]
	v_mov_b64_e32 v[58:59], v[8:9]
	v_mov_b64_e32 v[56:57], v[6:7]
	v_mov_b64_e32 v[54:55], v[4:5]
	v_mov_b64_e32 v[52:53], v[2:3]
	v_mov_b64_e32 v[50:51], v[0:1]
	v_mov_b64_e32 v[46:47], v[12:13]
	v_mov_b64_e32 v[44:45], v[10:11]
	v_mov_b64_e32 v[42:43], v[8:9]
	v_mov_b64_e32 v[40:41], v[6:7]
	v_mov_b64_e32 v[38:39], v[4:5]
	v_mov_b64_e32 v[36:37], v[2:3]
	v_mov_b64_e32 v[34:35], v[0:1]
	v_mov_b64_e32 v[30:31], v[12:13]
	v_mov_b64_e32 v[28:29], v[10:11]
	v_mov_b64_e32 v[26:27], v[8:9]
	v_mov_b64_e32 v[24:25], v[6:7]
	v_mov_b64_e32 v[22:23], v[4:5]
	v_mov_b64_e32 v[20:21], v[2:3]
	v_mov_b64_e32 v[18:19], v[0:1]
	v_mov_b64_e32 v[16:17], v[14:15]
	s_add_i32 s82, s64, s82
	s_mov_b32 s83, 0
	s_mov_b32 s84, 0
	s_mov_b32 s85, 0x10000
	v_mov_b64_e32 v[14:15], v[12:13]
	v_mov_b64_e32 v[12:13], v[10:11]
	v_mov_b64_e32 v[10:11], v[8:9]
	v_mov_b64_e32 v[8:9], v[6:7]
	v_mov_b64_e32 v[6:7], v[4:5]
	v_mov_b64_e32 v[4:5], v[2:3]
	v_mov_b64_e32 v[2:3], v[0:1]
	v_mov_b32_e32 v0, 0
	v_mov_b32_e32 v196, 0
	v_mov_b32_e32 v202, 0
	s_mov_b32 s86, 0
	v_mov_b32_e32 v66, 0
	v_mov_b32_e32 v67, v1
	v_mov_b32_e32 v68, v1
	v_mov_b32_e32 v69, v1
	v_mov_b32_e32 v70, v1
	v_mov_b32_e32 v71, v1
	v_mov_b32_e32 v72, v1
	v_mov_b32_e32 v73, v1
	v_mov_b32_e32 v74, v1
	v_mov_b32_e32 v75, v1
	v_mov_b32_e32 v76, v1
	v_mov_b32_e32 v77, v1
	v_mov_b32_e32 v78, v1
	v_mov_b32_e32 v79, v1
	v_mov_b32_e32 v80, v1
	v_mov_b32_e32 v81, v1
	s_mov_b32 s100, 0
	s_mov_b32 s98, 0xfffec000
	s_mov_b32 s99, -1
	v_lshl_add_u64 v[172:173], v[172:173], 0, s[98:99]
	s_mov_b32 s98, 0xfffcc000
	s_waitcnt vmcnt(10)
; #define ALAS __attribute__((address_space(3)))
; template <int N> __device__ __forceinline__ void wait_bar() { asm volatile("s_waitcnt vmcnt(%0) lgkmcnt(0)\n\ts_barrier" :: "n"(N) : "memory"); }
; template <bool WIN> ...
;     ...
;         if (tr + 2 < NT) wait_bar<2 * NPW>(); else if (tr + 1 < NT) wait_bar<NPW>(); else wait_bar<0>();
;         if (tr + 3 < NT) AT_DMA(tr + 3);
;         const int k0 = (t_lo + tr) * 64;
;         const bool skip = WIN && (k0 > qw + 31 + 128 || k0 + 63 < qw - 128);
;         if (!skip) {
;             const bool near = WIN || ((k0 - (qw + 31)) < 128 && (qw - (k0 + 63)) < 128);
;             const float cinit = near ? 0.f : (k0 > qw ? cfar_hi : cfar_lo);
;             if (__builtin_expect(cinit != cbase, 0)) { cbase = cinit; asm volatile("" ::: "memory");
; #pragma unroll
;                 for (int r = 0; r < 16; ++r) cvec[r] = cbase - m_ref; }
;             f32x16 s0, s1;
;             const ALAS unsigned char* sb = lds + (tr & (NSTG - 1)) * STAGE;
;             {
;                 bf16x8 ka[8];
; #pragma unroll
;                 for (int ds = 0; ds < 4; ++ds) { ka[2 * ds] = *(const ALAS bf16x8*)(sb + kx[ds]); ka[2 * ds + 1] = *(const ALAS bf16x8*)(sb + kx[ds] + 4096); }
;                 __builtin_amdgcn_sched_barrier(0);
;                 s0 = __builtin_amdgcn_mfma_f32_32x32x16_bf16(ka[0], qf(0), cvec, 0, 0, 0);
;                 s1 = __builtin_amdgcn_mfma_f32_32x32x16_bf16(ka[1], qf(0), cvec, 0, 0, 0);
; #pragma unroll
;                 for (int ds = 1; ds < 4; ++ds) {
;                     s0 = __builtin_amdgcn_mfma_f32_32x32x16_bf16(ka[2 * ds], qf(ds), s0, 0, 0, 0);
;                     s1 = __builtin_amdgcn_mfma_f32_32x32x16_bf16(ka[2 * ds + 1], qf(ds), s1, 0, 0, 0);
;                 }
;             }
;             bf16x8 va[2 * NDB], vc[2 * NDB];
; #pragma unroll
;             for (int kk = 0; kk < 2; ++kk)
; #pragma unroll
;                 for (int db = 0; db < NDB; ++db) va[kk * NDB + db] = *(const ALAS bf16x8*)(sb + vx[kk] + db * 4096);
;             __builtin_amdgcn_sched_barrier(0);
;             if (near) {
;                 const ALAS float* lb = lut + (k0 + 8 * hi - qabs + LUTC);
; #pragma unroll
;                 for (int r = 0; r < 16; ++r) { s0[r] += lb[16 * (r >> 3) + (r & 7)]; s1[r] += lb[32 + 16 * (r >> 3) + (r & 7)];
;                     if ((r & 7) == 7) __builtin_amdgcn_sched_barrier(0); }
;             }
	s_add_i32 s64, s81, s83
	s_max_i32 s64, s64, s82
	s_cmpk_lt_i32 s64, 0x80
	s_cselect_b64 s[64:65], -1, 0
	s_cmp_gt_i32 s83, s78
	s_cselect_b32 s87, s80, s79
	s_cmp_lg_u64 s[64:65], 0
	s_cselect_b32 m0, 0, s87
	s_cmp_lg_u64 s[64:65], 0
	s_cselect_b32 s65, 1, 0
	s_mov_b32 s87, 0
	s_mov_b32 s99, 0x18000
	s_add_i32 s98, s20, 0x18000
	s_add_i32 s101, s20, 0x10000
	v_lshl_add_u64 v[208:209], v[174:175], 0, s[40:41]
	v_lshl_add_u64 v[210:211], v[172:173], 0, s[40:41]
	v_add_u32_e32 v212, v178, v162
	v_add_u32_e32 v213, v180, v162
	v_add_u32_e32 v214, v182, v162
	v_add_u32_e32 v215, v184, v162
	s_branch .LSPp_top
.LSPp_top:
	s_cmpk_gt_u32 s86, 124
	s_cbranch_scc1 .LSPp_slowtop
	s_waitcnt vmcnt(8) lgkmcnt(0)
	s_barrier
	s_mov_b32 s64, s65
	s_cmp_eq_u32 m0, s100
	s_cbranch_scc0 .LSPp_cin
.LSPp_qk:
	ds_read_b128 v[130:133], v212
	ds_read_b128 v[134:137], v212 offset:4096
	ds_read_b128 v[138:141], v213
	ds_read_b128 v[142:145], v213 offset:4096
	ds_read_b128 v[146:149], v214
	ds_read_b128 v[150:153], v214 offset:4096
	ds_read_b128 v[158:161], v215
	ds_read_b128 v[204:207], v215 offset:4096
	s_mov_b32 m0, s98
	s_waitcnt lgkmcnt(0)
	v_mfma_f32_32x32x16_bf16 v[98:113], v[130:133], v[126:129], v[66:81]
	global_load_lds_dwordx4 v[174:175], off
	s_add_i32 m0, s98, 0x2000
	v_mfma_f32_32x32x16_bf16 v[82:97], v[134:137], v[126:129], v[66:81]
	global_load_lds_dwordx4 v[208:209], off
	s_add_i32 m0, s101, 0x4000
	v_mfma_f32_32x32x16_bf16 v[98:113], v[138:141], v[122:125], v[98:113]
	global_load_lds_dwordx4 v[172:173], off
	s_add_i32 m0, s101, 0x6000
	v_mfma_f32_32x32x16_bf16 v[82:97], v[142:145], v[122:125], v[82:97]
	global_load_lds_dwordx4 v[210:211], off
	v_mfma_f32_32x32x16_bf16 v[98:113], v[146:149], v[118:121], v[98:113]
	v_mfma_f32_32x32x16_bf16 v[82:97], v[150:153], v[118:121], v[82:97]
	v_mfma_f32_32x32x16_bf16 v[98:113], v[158:161], v[114:117], v[98:113]
	v_mfma_f32_32x32x16_bf16 v[82:97], v[204:207], v[114:117], v[82:97]
.LSPp_vrd:
	v_add3_u32 v236, s99, v179, v187
	ds_read_b128 v[146:149], v236 offset:16384
	ds_read_b128 v[150:153], v236 offset:20480
	ds_read_b128 v[154:157], v236 offset:24576
	ds_read_b128 v[158:161], v236 offset:28672
	v_add3_u32 v237, s99, v181, v187
	ds_read_b128 v[130:133], v237 offset:16384
	ds_read_b128 v[134:137], v237 offset:20480
	ds_read_b128 v[138:141], v237 offset:24576
	ds_read_b128 v[142:145], v237 offset:28672
	s_nop 1
	s_cmp_eq_u32 s64, 0
	s_cbranch_scc1 .LSPp_pv
	v_add_u32_e32 v203, s84, v171
	v_add_u32_e32 v204, 0x23b80, v203
	v_add_u32_e32 v206, 0x23c00, v203
	v_add_u32_e32 v210, 0x23c08, v203
	v_add_u32_e32 v208, 0x23b88, v203
	v_add_u32_e32 v218, 0x23c10, v203
	v_add_u32_e32 v212, 0x23b90, v203
	v_add_u32_e32 v216, 0x23c18, v203
	v_add_u32_e32 v214, 0x23b98, v203
	ds_read2_b32 v[204:205], v204 offset1:1
	ds_read2_b32 v[206:207], v206 offset1:1
	ds_read2_b32 v[208:209], v208 offset1:1
	ds_read2_b32 v[210:211], v210 offset1:1
	ds_read2_b32 v[212:213], v212 offset1:1
	ds_read2_b32 v[214:215], v214 offset1:1
	ds_read2_b32 v[216:217], v216 offset1:1
	ds_read2_b32 v[218:219], v218 offset1:1
	v_add_u32_e32 v220, 0x23bc0, v203
	v_add_u32_e32 v222, 0x23c40, v203
	v_add_u32_e32 v226, 0x23c48, v203
	v_add_u32_e32 v224, 0x23bc8, v203
	v_add_u32_e32 v228, 0x23bd0, v203
	v_add_u32_e32 v234, 0x23c58, v203
	ds_read2_b32 v[220:221], v220 offset1:1
	ds_read2_b32 v[222:223], v222 offset1:1
	ds_read2_b32 v[224:225], v224 offset1:1
	ds_read2_b32 v[226:227], v226 offset1:1
	v_add_u32_e32 v231, 0x23c50, v203
	v_add_u32_e32 v203, 0x23bd8, v203
	ds_read2_b32 v[228:229], v228 offset1:1
	ds_read2_b32 v[232:233], v203 offset1:1
	ds_read2_b32 v[234:235], v234 offset1:1
	ds_read2_b32 v[236:237], v231 offset1:1
	s_waitcnt lgkmcnt(10)
	v_pk_add_f32 v[104:105], v[104:105], v[214:215]
	v_pk_add_f32 v[102:103], v[102:103], v[212:213]
	v_pk_add_f32 v[100:101], v[100:101], v[208:209]
	s_waitcnt lgkmcnt(2)
	v_pk_add_f32 v[112:113], v[112:113], v[232:233]
	v_pk_add_f32 v[110:111], v[110:111], v[228:229]
	v_pk_add_f32 v[108:109], v[108:109], v[224:225]
	v_pk_add_f32 v[106:107], v[106:107], v[220:221]
	v_pk_add_f32 v[98:99], v[98:99], v[204:205]
	v_pk_add_f32 v[88:89], v[88:89], v[216:217]
	v_pk_add_f32 v[86:87], v[86:87], v[218:219]
	v_pk_add_f32 v[84:85], v[84:85], v[210:211]
	s_waitcnt lgkmcnt(1)
	v_pk_add_f32 v[96:97], v[96:97], v[234:235]
	s_waitcnt lgkmcnt(0)
	v_pk_add_f32 v[94:95], v[94:95], v[236:237]
	v_pk_add_f32 v[92:93], v[92:93], v[226:227]
	v_pk_add_f32 v[90:91], v[90:91], v[222:223]
	v_pk_add_f32 v[82:83], v[82:83], v[206:207]
; #define ALAS __attribute__((address_space(3)))
; template <bool WIN> ...
;     ...
;             float ls0 = 0.f, ls1 = 0.f;
;     ...
;             union PFU { u32x4 u; bf16x8 b; };
;             PFU p0, p1, p2, p3;
;             AT_EXP(s0, 0, p0);
; #pragma unroll
;             for (int kk = 0; kk < 2; ++kk)
; #pragma unroll
;                 for (int db = 0; db < NDB; ++db) vc[kk * NDB + db] = *(const ALAS bf16x8*)(sb + vx[kk + 2] + db * 4096);
;             __builtin_amdgcn_sched_barrier(0);
; #pragma unroll
;             for (int db = 0; db < NDB; ++db) o[db] = __builtin_amdgcn_mfma_f32_32x32x16_bf16(va[db], p0.b, o[db], 0, 0, 0);
;             AT_EXP(s0, 8, p1);
;             __builtin_amdgcn_sched_barrier(0);
; #pragma unroll
;             for (int db = 0; db < NDB; ++db) o[db] = __builtin_amdgcn_mfma_f32_32x32x16_bf16(va[NDB + db], p1.b, o[db], 0, 0, 0);
;             AT_EXP(s1, 0, p2);
;             __builtin_amdgcn_sched_barrier(0);
; #pragma unroll
;             for (int db = 0; db < NDB; ++db) o[db] = __builtin_amdgcn_mfma_f32_32x32x16_bf16(vc[db], p2.b, o[db], 0, 0, 0);
;             AT_EXP(s1, 8, p3);
;             __builtin_amdgcn_sched_barrier(0);
; #pragma unroll
;             for (int db = 0; db < NDB; ++db) o[db] = __builtin_amdgcn_mfma_f32_32x32x16_bf16(vc[NDB + db], p3.b, o[db], 0, 0, 0);
;             __builtin_amdgcn_sched_barrier(0);
;     ...
;             l_run += ls0 + ls1;
.LSPp_pv:
	s_cmp_eq_u32 s86, 0
	s_cbranch_scc1 .LSPp_pure
	s_waitcnt lgkmcnt(4)
	v_mfma_f32_32x32x16_bf16 v[50:65], v[146:149], v[238:241], v[50:65]
	v_exp_f32_e32 v98, v98
	v_exp_f32_e32 v99, v99
	v_exp_f32_e32 v100, v100
	v_mfma_f32_32x32x16_bf16 v[34:49], v[150:153], v[238:241], v[34:49]
	v_exp_f32_e32 v101, v101
	v_exp_f32_e32 v102, v102
	v_exp_f32_e32 v103, v103
	v_add_f32_e32 v228, v98, v99
	v_mov_b32_e32 v229, v100
	v_mfma_f32_32x32x16_bf16 v[18:33], v[154:157], v[238:241], v[18:33]
	v_exp_f32_e32 v104, v104
	v_exp_f32_e32 v105, v105
	v_exp_f32_e32 v106, v106
	v_add_f32_e32 v228, v228, v101
	v_add_f32_e32 v229, v229, v102
	v_add_f32_e32 v228, v228, v103
	v_mfma_f32_32x32x16_bf16 v[2:17], v[158:161], v[238:241], v[2:17]
	v_exp_f32_e32 v107, v107
	v_exp_f32_e32 v108, v108
	v_exp_f32_e32 v109, v109
	v_add_f32_e32 v229, v229, v104
	v_add_f32_e32 v228, v228, v105
	v_add_f32_e32 v229, v229, v106
	v_add3_u32 v236, s99, v183, v187
	ds_read_b128 v[146:149], v236 offset:16384
	ds_read_b128 v[150:153], v236 offset:20480
	ds_read_b128 v[154:157], v236 offset:24576
	ds_read_b128 v[158:161], v236 offset:28672
	s_waitcnt lgkmcnt(4)
	v_mfma_f32_32x32x16_bf16 v[50:65], v[130:133], v[242:245], v[50:65]
	v_exp_f32_e32 v110, v110
	v_exp_f32_e32 v111, v111
	v_exp_f32_e32 v112, v112
	v_add_f32_e32 v228, v228, v107
	v_add_f32_e32 v229, v229, v108
	v_add_f32_e32 v228, v228, v109
	v_cvt_pk_bf16_f32 v238, v98, v99
	v_lshl_add_u64 v[174:175], v[174:175], 0, s[60:61]
	v_lshl_add_u64 v[172:173], v[172:173], 0, s[48:49]
	s_add_i32 s98, s85, 0x10000
	v_mfma_f32_32x32x16_bf16 v[34:49], v[134:137], v[242:245], v[34:49]
	v_exp_f32_e32 v113, v113
	v_exp_f32_e32 v82, v82
	v_exp_f32_e32 v83, v83
	v_add_f32_e32 v229, v229, v110
	v_add_f32_e32 v228, v228, v111
	v_add_f32_e32 v229, v229, v112
	v_cvt_pk_bf16_f32 v239, v100, v101
	s_and_b32 s98, s98, 0x18000
	s_add_i32 s98, s98, s20
	s_add_i32 s101, s85, 0x8000
	v_mfma_f32_32x32x16_bf16 v[18:33], v[138:141], v[242:245], v[18:33]
	v_exp_f32_e32 v84, v84
	v_exp_f32_e32 v85, v85
	v_exp_f32_e32 v86, v86
	v_add_f32_e32 v228, v228, v113
	v_add_f32_e32 v229, v229, v82
	v_add_f32_e32 v228, v228, v83
	v_cvt_pk_bf16_f32 v240, v102, v103
	s_and_b32 s101, s101, 0x18000
	s_add_i32 s101, s101, s20
	v_lshl_add_u64 v[208:209], v[174:175], 0, s[40:41]
	v_mfma_f32_32x32x16_bf16 v[2:17], v[142:145], v[242:245], v[2:17]
	v_exp_f32_e32 v87, v87
	v_exp_f32_e32 v88, v88
	v_exp_f32_e32 v89, v89
	v_add_f32_e32 v229, v229, v84
	v_add_f32_e32 v228, v228, v85
	v_add_f32_e32 v229, v229, v86
	v_cvt_pk_bf16_f32 v241, v104, v105
	v_lshl_add_u64 v[210:211], v[172:173], 0, s[40:41]
	s_add_i32 s87, s85, 0xffff8000
	s_and_b32 s87, s87, 0x18000
	v_add3_u32 v237, s99, v190, v187
	ds_read_b128 v[130:133], v237 offset:16384
	ds_read_b128 v[134:137], v237 offset:20480
	ds_read_b128 v[138:141], v237 offset:24576
	ds_read_b128 v[142:145], v237 offset:28672
	s_waitcnt lgkmcnt(4)
	v_mfma_f32_32x32x16_bf16 v[50:65], v[146:149], v[246:249], v[50:65]
	v_exp_f32_e32 v90, v90
	v_exp_f32_e32 v91, v91
	v_exp_f32_e32 v92, v92
	v_add_f32_e32 v228, v228, v87
	v_add_f32_e32 v229, v229, v88
	v_add_f32_e32 v228, v228, v89
	v_cvt_pk_bf16_f32 v242, v106, v107
	v_add3_u32 v212, s87, v178, v162
	v_add3_u32 v213, s87, v180, v162
	v_add3_u32 v214, s87, v182, v162
	v_mfma_f32_32x32x16_bf16 v[34:49], v[150:153], v[246:249], v[34:49]
	v_exp_f32_e32 v93, v93
	v_exp_f32_e32 v94, v94
	v_exp_f32_e32 v95, v95
	v_add_f32_e32 v229, v229, v90
	v_add_f32_e32 v228, v228, v91
	v_add_f32_e32 v229, v229, v92
	v_cvt_pk_bf16_f32 v243, v108, v109
	v_add3_u32 v215, s87, v184, v162
	s_add_i32 s99, s81, s83
	s_add_i32 s99, s99, 64
	v_mfma_f32_32x32x16_bf16 v[18:33], v[154:157], v[246:249], v[18:33]
	v_exp_f32_e32 v96, v96
	v_exp_f32_e32 v97, v97
	v_add_f32_e32 v228, v228, v93
	v_add_f32_e32 v229, v229, v94
	v_add_f32_e32 v228, v228, v95
	v_cvt_pk_bf16_f32 v244, v110, v111
	s_sub_i32 m0, s82, 64
	s_max_i32 s99, s99, m0
	s_add_i32 m0, s83, 64
	v_mfma_f32_32x32x16_bf16 v[2:17], v[158:161], v[246:249], v[2:17]
	v_add_f32_e32 v229, v229, v96
	v_add_f32_e32 v228, v228, v97
	v_cvt_pk_bf16_f32 v245, v112, v113
	s_cmp_gt_i32 m0, s78
	s_cselect_b32 m0, s80, s79
	s_cmpk_lt_i32 s99, 0x80
	s_waitcnt lgkmcnt(0)
	v_mfma_f32_32x32x16_bf16 v[50:65], v[130:133], v[250:253], v[50:65]
	v_cvt_pk_bf16_f32 v246, v82, v83
	s_cselect_b32 s65, 1, 0
	s_cselect_b32 m0, 0, m0
	s_add_i32 s99, s85, 0xffff0000
	v_mfma_f32_32x32x16_bf16 v[34:49], v[134:137], v[250:253], v[34:49]
	v_cvt_pk_bf16_f32 v247, v84, v85
	s_and_b32 s99, s99, 0x18000
	v_mfma_f32_32x32x16_bf16 v[18:33], v[138:141], v[250:253], v[18:33]
	v_cvt_pk_bf16_f32 v248, v86, v87
	v_mfma_f32_32x32x16_bf16 v[2:17], v[142:145], v[250:253], v[2:17]
	v_cvt_pk_bf16_f32 v249, v88, v89
	v_cvt_pk_bf16_f32 v250, v90, v91
	v_cvt_pk_bf16_f32 v251, v92, v93
	v_cvt_pk_bf16_f32 v252, v94, v95
	v_cvt_pk_bf16_f32 v253, v96, v97
	v_add_f32_e32 v228, v228, v229
	v_cmp_nge_f32_e32 vcc, 0x53800000, v228
	s_cbranch_vccnz .LSPp_redo
	s_add_i32 s86, s86, 1
	s_add_i32 s85, s85, 0x8000
	s_addk_i32 s84, 0x100
	s_add_i32 s83, s83, 64
	s_sub_i32 s82, s82, 64
	v_add_f32_e32 v0, v0, v228
	s_cmpk_eq_u32 s84, 0x8000
	s_cbranch_scc0 .LSPp_top
	s_branch .LSPp_exit
; template <bool WIN> ...
;     ...
;             {
;                 bf16x8 ka[8];
; #pragma unroll
;                 for (int ds = 0; ds < 4; ++ds) { ka[2 * ds] = *(const ALAS bf16x8*)(sb + kx[ds]); ka[2 * ds + 1] = *(const ALAS bf16x8*)(sb + kx[ds] + 4096); }
;                 __builtin_amdgcn_sched_barrier(0);
;                 s0 = __builtin_amdgcn_mfma_f32_32x32x16_bf16(ka[0], qf(0), cvec, 0, 0, 0);
;                 s1 = __builtin_amdgcn_mfma_f32_32x32x16_bf16(ka[1], qf(0), cvec, 0, 0, 0);
; #pragma unroll
;                 for (int ds = 1; ds < 4; ++ds) {
;                     s0 = __builtin_amdgcn_mfma_f32_32x32x16_bf16(ka[2 * ds], qf(ds), s0, 0, 0, 0);
;                     s1 = __builtin_amdgcn_mfma_f32_32x32x16_bf16(ka[2 * ds + 1], qf(ds), s1, 0, 0, 0);
;                 }
;             }
;             bf16x8 va[2 * NDB], vc[2 * NDB];
; #pragma unroll
;             for (int kk = 0; kk < 2; ++kk)
; #pragma unroll
;                 for (int db = 0; db < NDB; ++db) va[kk * NDB + db] = *(const ALAS bf16x8*)(sb + vx[kk] + db * 4096);
;     ...
;             float ls0 = 0.f, ls1 = 0.f;
;     ...
;             union PFU { u32x4 u; bf16x8 b; };
;             PFU p0, p1, p2, p3;
;             AT_EXP(s0, 0, p0);
; #pragma unroll
;             for (int kk = 0; kk < 2; ++kk)
; #pragma unroll
;                 for (int db = 0; db < NDB; ++db) vc[kk * NDB + db] = *(const ALAS bf16x8*)(sb + vx[kk + 2] + db * 4096);
;             __builtin_amdgcn_sched_barrier(0);
; #pragma unroll
;             for (int db = 0; db < NDB; ++db) o[db] = __builtin_amdgcn_mfma_f32_32x32x16_bf16(va[db], p0.b, o[db], 0, 0, 0);
;             AT_EXP(s0, 8, p1);
;             __builtin_amdgcn_sched_barrier(0);
; #pragma unroll
;             for (int db = 0; db < NDB; ++db) o[db] = __builtin_amdgcn_mfma_f32_32x32x16_bf16(va[NDB + db], p1.b, o[db], 0, 0, 0);
;             AT_EXP(s1, 0, p2);
;             __builtin_amdgcn_sched_barrier(0);
; #pragma unroll
;             for (int db = 0; db < NDB; ++db) o[db] = __builtin_amdgcn_mfma_f32_32x32x16_bf16(vc[db], p2.b, o[db], 0, 0, 0);
;             AT_EXP(s1, 8, p3);
;             __builtin_amdgcn_sched_barrier(0);
; #pragma unroll
;             for (int db = 0; db < NDB; ++db) o[db] = __builtin_amdgcn_mfma_f32_32x32x16_bf16(vc[NDB + db], p3.b, o[db], 0, 0, 0);
;             __builtin_amdgcn_sched_barrier(0);
;     ...
;             l_run += ls0 + ls1;
.LSPp_pure:
	v_lshl_add_u64 v[174:175], v[174:175], 0, s[60:61]
	v_lshl_add_u64 v[172:173], v[172:173], 0, s[48:49]
	s_add_i32 s98, s85, 0x10000
	s_and_b32 s98, s98, 0x18000
	s_add_i32 s98, s98, s20
	s_add_i32 s101, s85, 0x8000
	s_and_b32 s101, s101, 0x18000
	s_add_i32 s101, s101, s20
	v_lshl_add_u64 v[208:209], v[174:175], 0, s[40:41]
	v_lshl_add_u64 v[210:211], v[172:173], 0, s[40:41]
	s_add_i32 s87, s85, 0xffff8000
	s_and_b32 s87, s87, 0x18000
	v_add3_u32 v212, s87, v178, v162
	v_add3_u32 v213, s87, v180, v162
	v_add3_u32 v214, s87, v182, v162
	v_add3_u32 v215, s87, v184, v162
	s_add_i32 s99, s81, s83
	s_add_i32 s99, s99, 64
	s_sub_i32 m0, s82, 64
	s_max_i32 s99, s99, m0
	s_add_i32 m0, s83, 64
	s_cmp_gt_i32 m0, s78
	s_cselect_b32 m0, s80, s79
	s_cmpk_lt_i32 s99, 0x80
	s_cselect_b32 s65, 1, 0
	s_cselect_b32 m0, 0, m0
	s_add_i32 s99, s85, 0xffff0000
	s_and_b32 s99, s99, 0x18000
	v_exp_f32_e32 v98, v98
	v_exp_f32_e32 v99, v99
	v_exp_f32_e32 v100, v100
	v_exp_f32_e32 v101, v101
	v_exp_f32_e32 v102, v102
	v_exp_f32_e32 v103, v103
	v_exp_f32_e32 v104, v104
	v_exp_f32_e32 v105, v105
	v_cvt_pk_bf16_f32 v238, v98, v99
	v_cvt_pk_bf16_f32 v239, v100, v101
	v_cvt_pk_bf16_f32 v240, v102, v103
	v_cvt_pk_bf16_f32 v241, v104, v105
	v_mov_b32_e32 v228, v98
	v_mov_b32_e32 v229, v102
	v_add_f32_e32 v228, v228, v99
	v_add_f32_e32 v229, v229, v103
	v_add_f32_e32 v228, v228, v100
	v_add_f32_e32 v229, v229, v104
	v_add_f32_e32 v228, v228, v101
	v_add_f32_e32 v229, v229, v105
	v_exp_f32_e32 v106, v106
	v_exp_f32_e32 v107, v107
	v_exp_f32_e32 v108, v108
	v_exp_f32_e32 v109, v109
	v_exp_f32_e32 v110, v110
	v_exp_f32_e32 v111, v111
	v_exp_f32_e32 v112, v112
	v_exp_f32_e32 v113, v113
	v_cvt_pk_bf16_f32 v242, v106, v107
	v_cvt_pk_bf16_f32 v243, v108, v109
	v_cvt_pk_bf16_f32 v244, v110, v111
	v_cvt_pk_bf16_f32 v245, v112, v113
	v_add_f32_e32 v228, v228, v106
	v_add_f32_e32 v229, v229, v110
	v_add_f32_e32 v228, v228, v107
	v_add_f32_e32 v229, v229, v111
	v_add_f32_e32 v228, v228, v108
	v_add_f32_e32 v229, v229, v112
	v_add_f32_e32 v228, v228, v109
	v_add_f32_e32 v229, v229, v113
	v_exp_f32_e32 v82, v82
	v_exp_f32_e32 v83, v83
	v_exp_f32_e32 v84, v84
	v_exp_f32_e32 v85, v85
	v_exp_f32_e32 v86, v86
	v_exp_f32_e32 v87, v87
	v_exp_f32_e32 v88, v88
	v_exp_f32_e32 v89, v89
	v_cvt_pk_bf16_f32 v246, v82, v83
	v_cvt_pk_bf16_f32 v247, v84, v85
	v_cvt_pk_bf16_f32 v248, v86, v87
	v_cvt_pk_bf16_f32 v249, v88, v89
	v_add_f32_e32 v228, v228, v82
	v_add_f32_e32 v229, v229, v86
	v_add_f32_e32 v228, v228, v83
	v_add_f32_e32 v229, v229, v87
	v_add_f32_e32 v228, v228, v84
	v_add_f32_e32 v229, v229, v88
	v_add_f32_e32 v228, v228, v85
	v_add_f32_e32 v229, v229, v89
	v_exp_f32_e32 v90, v90
	v_exp_f32_e32 v91, v91
	v_exp_f32_e32 v92, v92
	v_exp_f32_e32 v93, v93
	v_exp_f32_e32 v94, v94
	v_exp_f32_e32 v95, v95
	v_exp_f32_e32 v96, v96
	v_exp_f32_e32 v97, v97
	v_cvt_pk_bf16_f32 v250, v90, v91
	v_cvt_pk_bf16_f32 v251, v92, v93
	v_cvt_pk_bf16_f32 v252, v94, v95
	v_cvt_pk_bf16_f32 v253, v96, v97
	v_add_f32_e32 v228, v228, v90
	v_add_f32_e32 v229, v229, v94
	v_add_f32_e32 v228, v228, v91
	v_add_f32_e32 v229, v229, v95
	v_add_f32_e32 v228, v228, v92
	v_add_f32_e32 v229, v229, v96
	v_add_f32_e32 v228, v228, v93
	v_add_f32_e32 v229, v229, v97
	v_add_f32_e32 v228, v228, v229
	v_cmp_nge_f32_e32 vcc, 0x53800000, v228
	s_cbranch_vccnz .LSPp_redo
	s_add_i32 s86, s86, 1
	s_add_i32 s85, s85, 0x8000
	s_addk_i32 s84, 0x100
	s_add_i32 s83, s83, 64
	s_sub_i32 s82, s82, 64
	v_add_f32_e32 v0, v0, v228
	s_cmpk_eq_u32 s84, 0x8000
	s_cbranch_scc0 .LSPp_top
	s_branch .LSPp_exit
.LSPp_redo:
	s_add_i32 s87, s85, 0xffff0000
	s_and_b32 s87, s87, 0x18000
	v_add3_u32 v203, s87, v178, v162
	ds_read_b128 v[130:133], v203
	ds_read_b128 v[134:137], v203 offset:4096
	v_add3_u32 v203, s87, v180, v162
	ds_read_b128 v[138:141], v203
	ds_read_b128 v[142:145], v203 offset:4096
	v_add3_u32 v203, s87, v182, v162
	ds_read_b128 v[146:149], v203
	ds_read_b128 v[150:153], v203 offset:4096
	v_add3_u32 v203, s87, v184, v162
	ds_read_b128 v[158:161], v203
	ds_read_b128 v[204:207], v203 offset:4096
	s_waitcnt lgkmcnt(0)
	v_mfma_f32_32x32x16_bf16 v[98:113], v[130:133], v[126:129], v[66:81]
	v_mfma_f32_32x32x16_bf16 v[82:97], v[134:137], v[126:129], v[66:81]
	v_mfma_f32_32x32x16_bf16 v[98:113], v[138:141], v[122:125], v[98:113]
	v_mfma_f32_32x32x16_bf16 v[82:97], v[142:145], v[122:125], v[82:97]
	v_mfma_f32_32x32x16_bf16 v[98:113], v[146:149], v[118:121], v[98:113]
	v_mfma_f32_32x32x16_bf16 v[82:97], v[150:153], v[118:121], v[82:97]
	v_mfma_f32_32x32x16_bf16 v[98:113], v[158:161], v[114:117], v[98:113]
	v_mfma_f32_32x32x16_bf16 v[82:97], v[204:207], v[114:117], v[82:97]
	s_nop 7
	s_nop 7
	s_cmp_eq_u32 s64, 0
	s_cbranch_scc1 .LSPp_redomax
	v_add_u32_e32 v203, s84, v171
	v_add_u32_e32 v204, 0x23b80, v203
	v_add_u32_e32 v206, 0x23c00, v203
	v_add_u32_e32 v210, 0x23c08, v203
	v_add_u32_e32 v208, 0x23b88, v203
	v_add_u32_e32 v218, 0x23c10, v203
	v_add_u32_e32 v212, 0x23b90, v203
	v_add_u32_e32 v216, 0x23c18, v203
	v_add_u32_e32 v214, 0x23b98, v203
	ds_read2_b32 v[204:205], v204 offset1:1
	ds_read2_b32 v[206:207], v206 offset1:1
	ds_read2_b32 v[208:209], v208 offset1:1
	ds_read2_b32 v[210:211], v210 offset1:1
	ds_read2_b32 v[212:213], v212 offset1:1
	ds_read2_b32 v[214:215], v214 offset1:1
	ds_read2_b32 v[216:217], v216 offset1:1
	ds_read2_b32 v[218:219], v218 offset1:1
	v_add_u32_e32 v220, 0x23bc0, v203
	v_add_u32_e32 v222, 0x23c40, v203
	v_add_u32_e32 v226, 0x23c48, v203
	v_add_u32_e32 v224, 0x23bc8, v203
	v_add_u32_e32 v228, 0x23bd0, v203
	v_add_u32_e32 v234, 0x23c58, v203
	ds_read2_b32 v[220:221], v220 offset1:1
	ds_read2_b32 v[222:223], v222 offset1:1
	ds_read2_b32 v[224:225], v224 offset1:1
	ds_read2_b32 v[226:227], v226 offset1:1
	v_add_u32_e32 v231, 0x23c50, v203
	v_add_u32_e32 v203, 0x23bd8, v203
	ds_read2_b32 v[228:229], v228 offset1:1
	ds_read2_b32 v[232:233], v203 offset1:1
	ds_read2_b32 v[234:235], v234 offset1:1
	ds_read2_b32 v[236:237], v231 offset1:1
	s_waitcnt lgkmcnt(10)
	v_pk_add_f32 v[104:105], v[104:105], v[214:215]
	v_pk_add_f32 v[102:103], v[102:103], v[212:213]
	v_pk_add_f32 v[100:101], v[100:101], v[208:209]
	s_waitcnt lgkmcnt(2)
	v_pk_add_f32 v[112:113], v[112:113], v[232:233]
	v_pk_add_f32 v[110:111], v[110:111], v[228:229]
	v_pk_add_f32 v[108:109], v[108:109], v[224:225]
	v_pk_add_f32 v[106:107], v[106:107], v[220:221]
	v_pk_add_f32 v[98:99], v[98:99], v[204:205]
	v_pk_add_f32 v[88:89], v[88:89], v[216:217]
	v_pk_add_f32 v[86:87], v[86:87], v[218:219]
	v_pk_add_f32 v[84:85], v[84:85], v[210:211]
	s_waitcnt lgkmcnt(1)
	v_pk_add_f32 v[96:97], v[96:97], v[234:235]
	s_waitcnt lgkmcnt(0)
	v_pk_add_f32 v[94:95], v[94:95], v[236:237]
	v_pk_add_f32 v[92:93], v[92:93], v[226:227]
	v_pk_add_f32 v[90:91], v[90:91], v[222:223]
	v_pk_add_f32 v[82:83], v[82:83], v[206:207]

; #define ALAS __attribute__((address_space(3)))
; template <int N> __device__ __forceinline__ void wait_bar() { asm volatile("s_waitcnt vmcnt(%0) lgkmcnt(0)\n\ts_barrier" :: "n"(N) : "memory"); }
; template <bool WIN> ...
;     ...
;         if (tr + 2 < NT) wait_bar<2 * NPW>(); else if (tr + 1 < NT) wait_bar<NPW>(); else wait_bar<0>();
;         if (tr + 3 < NT) AT_DMA(tr + 3);
;         const int k0 = (t_lo + tr) * 64;
;         const bool skip = WIN && (k0 > qw + 31 + 128 || k0 + 63 < qw - 128);
;         if (!skip) {
;             const bool near = WIN || ((k0 - (qw + 31)) < 128 && (qw - (k0 + 63)) < 128);
;             const float cinit = near ? 0.f : (k0 > qw ? cfar_hi : cfar_lo);
;             if (__builtin_expect(cinit != cbase, 0)) { cbase = cinit; asm volatile("" ::: "memory");
; #pragma unroll
;                 for (int r = 0; r < 16; ++r) cvec[r] = cbase - m_ref; }
;     ...
;             float ls0 = 0.f, ls1 = 0.f;
;     ...
;             union PFU { u32x4 u; bf16x8 b; };
;             PFU p0, p1, p2, p3;
;             AT_EXP(s0, 0, p0);
; #pragma unroll
;             for (int kk = 0; kk < 2; ++kk)
; #pragma unroll
;                 for (int db = 0; db < NDB; ++db) vc[kk * NDB + db] = *(const ALAS bf16x8*)(sb + vx[kk + 2] + db * 4096);
;             __builtin_amdgcn_sched_barrier(0);
; #pragma unroll
;             for (int db = 0; db < NDB; ++db) o[db] = __builtin_amdgcn_mfma_f32_32x32x16_bf16(va[db], p0.b, o[db], 0, 0, 0);
;             AT_EXP(s0, 8, p1);
;             __builtin_amdgcn_sched_barrier(0);
; #pragma unroll
;             for (int db = 0; db < NDB; ++db) o[db] = __builtin_amdgcn_mfma_f32_32x32x16_bf16(va[NDB + db], p1.b, o[db], 0, 0, 0);
;             AT_EXP(s1, 0, p2);
;             __builtin_amdgcn_sched_barrier(0);
; #pragma unroll
;             for (int db = 0; db < NDB; ++db) o[db] = __builtin_amdgcn_mfma_f32_32x32x16_bf16(vc[db], p2.b, o[db], 0, 0, 0);
;             AT_EXP(s1, 8, p3);
;             __builtin_amdgcn_sched_barrier(0);
; #pragma unroll
;             for (int db = 0; db < NDB; ++db) o[db] = __builtin_amdgcn_mfma_f32_32x32x16_bf16(vc[NDB + db], p3.b, o[db], 0, 0, 0);
;             __builtin_amdgcn_sched_barrier(0);
;     ...
;             l_run += ls0 + ls1;
.LSPp_pure2:
	s_add_i32 s87, s85, 0xffff8000
	s_and_b32 s87, s87, 0x18000
	v_lshl_add_u64 v[208:209], v[174:175], 0, s[40:41]
	v_lshl_add_u64 v[210:211], v[172:173], 0, s[40:41]
	v_add3_u32 v212, s87, v178, v162
	v_add3_u32 v213, s87, v180, v162
	v_add3_u32 v214, s87, v182, v162
	v_add3_u32 v215, s87, v184, v162
	v_exp_f32_e32 v98, v98
	v_exp_f32_e32 v99, v99
	v_exp_f32_e32 v100, v100
	v_exp_f32_e32 v101, v101
	v_exp_f32_e32 v102, v102
	v_exp_f32_e32 v103, v103
	v_exp_f32_e32 v104, v104
	v_exp_f32_e32 v105, v105
	v_cvt_pk_bf16_f32 v238, v98, v99
	v_cvt_pk_bf16_f32 v239, v100, v101
	v_cvt_pk_bf16_f32 v240, v102, v103
	v_cvt_pk_bf16_f32 v241, v104, v105
	v_mov_b32_e32 v228, v98
	v_mov_b32_e32 v229, v102
	v_add_f32_e32 v228, v228, v99
	v_add_f32_e32 v229, v229, v103
	v_add_f32_e32 v228, v228, v100
	v_add_f32_e32 v229, v229, v104
	v_add_f32_e32 v228, v228, v101
	v_add_f32_e32 v229, v229, v105
	v_exp_f32_e32 v106, v106
	v_exp_f32_e32 v107, v107
	v_exp_f32_e32 v108, v108
	v_exp_f32_e32 v109, v109
	v_exp_f32_e32 v110, v110
	v_exp_f32_e32 v111, v111
	v_exp_f32_e32 v112, v112
	v_exp_f32_e32 v113, v113
	v_cvt_pk_bf16_f32 v242, v106, v107
	v_cvt_pk_bf16_f32 v243, v108, v109
	v_cvt_pk_bf16_f32 v244, v110, v111
	v_cvt_pk_bf16_f32 v245, v112, v113
	v_add_f32_e32 v228, v228, v106
	v_add_f32_e32 v229, v229, v110
	v_add_f32_e32 v228, v228, v107
	v_add_f32_e32 v229, v229, v111
	v_add_f32_e32 v228, v228, v108
	v_add_f32_e32 v229, v229, v112
	v_add_f32_e32 v228, v228, v109
	v_add_f32_e32 v229, v229, v113
	v_exp_f32_e32 v82, v82
	v_exp_f32_e32 v83, v83
	v_exp_f32_e32 v84, v84
	v_exp_f32_e32 v85, v85
	v_exp_f32_e32 v86, v86
	v_exp_f32_e32 v87, v87
	v_exp_f32_e32 v88, v88
	v_exp_f32_e32 v89, v89
	v_cvt_pk_bf16_f32 v246, v82, v83
	v_cvt_pk_bf16_f32 v247, v84, v85
	v_cvt_pk_bf16_f32 v248, v86, v87
	v_cvt_pk_bf16_f32 v249, v88, v89
	v_add_f32_e32 v228, v228, v82
	v_add_f32_e32 v229, v229, v86
	v_add_f32_e32 v228, v228, v83
	v_add_f32_e32 v229, v229, v87
	v_add_f32_e32 v228, v228, v84
	v_add_f32_e32 v229, v229, v88
	v_add_f32_e32 v228, v228, v85
	v_add_f32_e32 v229, v229, v89
	v_exp_f32_e32 v90, v90
	v_exp_f32_e32 v91, v91
	v_exp_f32_e32 v92, v92
	v_exp_f32_e32 v93, v93
	v_exp_f32_e32 v94, v94
	v_exp_f32_e32 v95, v95
	v_exp_f32_e32 v96, v96
	v_exp_f32_e32 v97, v97
	v_cvt_pk_bf16_f32 v250, v90, v91
	v_cvt_pk_bf16_f32 v251, v92, v93
	v_cvt_pk_bf16_f32 v252, v94, v95
	v_cvt_pk_bf16_f32 v253, v96, v97
	v_add_f32_e32 v228, v228, v90
	v_add_f32_e32 v229, v229, v94
	v_add_f32_e32 v228, v228, v91
	v_add_f32_e32 v229, v229, v95
	v_add_f32_e32 v228, v228, v92
	v_add_f32_e32 v229, v229, v96
	v_add_f32_e32 v228, v228, v93
	v_add_f32_e32 v229, v229, v97
	v_add_f32_e32 v228, v228, v229
	s_add_i32 s86, s86, 1
	s_add_i32 s85, s85, 0x8000
	s_addk_i32 s84, 0x100
	s_add_i32 s83, s83, 64
	s_sub_i32 s82, s82, 64
	v_add_f32_e32 v0, v0, v228
	s_cmpk_eq_u32 s84, 0x8000
	s_cbranch_scc0 .LSPp_top
	s_branch .LSPp_exit
.LSPp_exit:
	s_add_i32 s99, s85, 0xfffe8000
	s_and_b32 s99, s99, 0x18000
	v_add3_u32 v236, s99, v179, v187
	ds_read_b128 v[146:149], v236 offset:16384
	ds_read_b128 v[150:153], v236 offset:20480
	ds_read_b128 v[154:157], v236 offset:24576
	ds_read_b128 v[158:161], v236 offset:28672
	v_add3_u32 v237, s99, v181, v187
	ds_read_b128 v[130:133], v237 offset:16384
	ds_read_b128 v[134:137], v237 offset:20480
	ds_read_b128 v[138:141], v237 offset:24576
	ds_read_b128 v[142:145], v237 offset:28672
	s_waitcnt lgkmcnt(4)
	v_mfma_f32_32x32x16_bf16 v[50:65], v[146:149], v[238:241], v[50:65]
	v_mfma_f32_32x32x16_bf16 v[34:49], v[150:153], v[238:241], v[34:49]
	v_mfma_f32_32x32x16_bf16 v[18:33], v[154:157], v[238:241], v[18:33]
	v_mfma_f32_32x32x16_bf16 v[2:17], v[158:161], v[238:241], v[2:17]
	v_add3_u32 v236, s99, v183, v187
	ds_read_b128 v[146:149], v236 offset:16384
	ds_read_b128 v[150:153], v236 offset:20480
	ds_read_b128 v[154:157], v236 offset:24576
	ds_read_b128 v[158:161], v236 offset:28672
	s_waitcnt lgkmcnt(4)
	v_mfma_f32_32x32x16_bf16 v[50:65], v[130:133], v[242:245], v[50:65]
	v_mfma_f32_32x32x16_bf16 v[34:49], v[134:137], v[242:245], v[34:49]
	v_mfma_f32_32x32x16_bf16 v[18:33], v[138:141], v[242:245], v[18:33]
	v_mfma_f32_32x32x16_bf16 v[2:17], v[142:145], v[242:245], v[2:17]
	v_add3_u32 v237, s99, v190, v187
	ds_read_b128 v[130:133], v237 offset:16384
	ds_read_b128 v[134:137], v237 offset:20480
	ds_read_b128 v[138:141], v237 offset:24576
	ds_read_b128 v[142:145], v237 offset:28672
	s_waitcnt lgkmcnt(4)
	v_mfma_f32_32x32x16_bf16 v[50:65], v[146:149], v[246:249], v[50:65]
	v_mfma_f32_32x32x16_bf16 v[34:49], v[150:153], v[246:249], v[34:49]
	v_mfma_f32_32x32x16_bf16 v[18:33], v[154:157], v[246:249], v[18:33]
	v_mfma_f32_32x32x16_bf16 v[2:17], v[158:161], v[246:249], v[2:17]
	s_waitcnt lgkmcnt(0)
	v_mfma_f32_32x32x16_bf16 v[50:65], v[130:133], v[250:253], v[50:65]
	v_mfma_f32_32x32x16_bf16 v[34:49], v[134:137], v[250:253], v[34:49]
	v_mfma_f32_32x32x16_bf16 v[18:33], v[138:141], v[250:253], v[18:33]
	v_mfma_f32_32x32x16_bf16 v[2:17], v[142:145], v[250:253], v[2:17]
	s_branch .LBB0_262
.LSPp_slowtop:
	s_cmpk_gt_u32 s86, 125
	s_cbranch_scc1 .LSPp_t0
	s_waitcnt vmcnt(8) lgkmcnt(0)
	s_barrier
.LSPp_t0d:
	s_mov_b32 s64, s65
	s_cmp_eq_u32 m0, s100
	s_cbranch_scc0 .LSPp_cin2

; #define ALAS __attribute__((address_space(3)))
; template <bool WIN> ...
;     ...
;             {
;                 bf16x8 ka[8];
; #pragma unroll
;                 for (int ds = 0; ds < 4; ++ds) { ka[2 * ds] = *(const ALAS bf16x8*)(sb + kx[ds]); ka[2 * ds + 1] = *(const ALAS bf16x8*)(sb + kx[ds] + 4096); }
;                 __builtin_amdgcn_sched_barrier(0);
;                 s0 = __builtin_amdgcn_mfma_f32_32x32x16_bf16(ka[0], qf(0), cvec, 0, 0, 0);
;                 s1 = __builtin_amdgcn_mfma_f32_32x32x16_bf16(ka[1], qf(0), cvec, 0, 0, 0);
; #pragma unroll
;                 for (int ds = 1; ds < 4; ++ds) {
;                     s0 = __builtin_amdgcn_mfma_f32_32x32x16_bf16(ka[2 * ds], qf(ds), s0, 0, 0, 0);
;                     s1 = __builtin_amdgcn_mfma_f32_32x32x16_bf16(ka[2 * ds + 1], qf(ds), s1, 0, 0, 0);
;                 }
;             }
.LSPp_skipv:
	ds_read_b128 v[130:133], v212
	ds_read_b128 v[134:137], v212 offset:4096
	ds_read_b128 v[138:141], v213
	ds_read_b128 v[142:145], v213 offset:4096
	ds_read_b128 v[146:149], v214
	ds_read_b128 v[150:153], v214 offset:4096
	ds_read_b128 v[158:161], v215
	ds_read_b128 v[204:207], v215 offset:4096
	s_waitcnt lgkmcnt(0)
	v_mfma_f32_32x32x16_bf16 v[98:113], v[130:133], v[126:129], v[66:81]
	v_mfma_f32_32x32x16_bf16 v[82:97], v[134:137], v[126:129], v[66:81]
	v_mfma_f32_32x32x16_bf16 v[98:113], v[138:141], v[122:125], v[98:113]
	v_mfma_f32_32x32x16_bf16 v[82:97], v[142:145], v[122:125], v[82:97]
	v_mfma_f32_32x32x16_bf16 v[98:113], v[146:149], v[118:121], v[98:113]
	v_mfma_f32_32x32x16_bf16 v[82:97], v[150:153], v[118:121], v[82:97]
	v_mfma_f32_32x32x16_bf16 v[98:113], v[158:161], v[114:117], v[98:113]
	v_mfma_f32_32x32x16_bf16 v[82:97], v[204:207], v[114:117], v[82:97]
	s_branch .LSPp_vrd

; template <bool WIN> ...
;     ...
;             const float cinit = near ? 0.f : (k0 > qw ? cfar_hi : cfar_lo);
;             if (__builtin_expect(cinit != cbase, 0)) { cbase = cinit; asm volatile("" ::: "memory");
; #pragma unroll
;                 for (int r = 0; r < 16; ++r) cvec[r] = cbase - m_ref; }
.LSPp_cin:
	v_mov_b32_e32 v98, m0
	s_mov_b32 s100, m0
	v_sub_f32_e32 v82, v98, v196
	v_mov_b32_e32 v202, v98
	v_mov_b32_e32 v66, v82
	v_mov_b32_e32 v67, v82
	v_mov_b32_e32 v68, v82
	v_mov_b32_e32 v69, v82
	v_mov_b32_e32 v70, v82
	v_mov_b32_e32 v71, v82
	v_mov_b32_e32 v72, v82
	v_mov_b32_e32 v73, v82
	v_mov_b32_e32 v74, v82
	v_mov_b32_e32 v75, v82
	v_mov_b32_e32 v76, v82
	v_mov_b32_e32 v77, v82
	v_mov_b32_e32 v78, v82
	v_mov_b32_e32 v79, v82
	v_mov_b32_e32 v80, v82
	v_mov_b32_e32 v81, v82
	s_branch .LSPp_qk
.LSPp_cin2:
	v_mov_b32_e32 v98, m0
	s_mov_b32 s100, m0
	v_sub_f32_e32 v82, v98, v196
	v_mov_b32_e32 v202, v98
	v_mov_b32_e32 v66, v82
	v_mov_b32_e32 v67, v82
	v_mov_b32_e32 v68, v82
	v_mov_b32_e32 v69, v82
	v_mov_b32_e32 v70, v82
	v_mov_b32_e32 v71, v82
	v_mov_b32_e32 v72, v82
	v_mov_b32_e32 v73, v82
	v_mov_b32_e32 v74, v82
	v_mov_b32_e32 v75, v82
	v_mov_b32_e32 v76, v82
	v_mov_b32_e32 v77, v82
	v_mov_b32_e32 v78, v82
	v_mov_b32_e32 v79, v82
	v_mov_b32_e32 v80, v82
	v_mov_b32_e32 v81, v82
	s_branch .LSPp_sqk

; template <bool WIN> ...
;     ...
;     const bf16_t* kg = QK + ((size_t)((seq_base >> 6) + t_lo) * 26 * 64 + drow) * 64 + dch * 8 + kcol0 * 64;
;     const bf16_t* vg = VT + ((size_t)((seq_base >> 6) + t_lo) * 640 + vrow0 + drow) * 64 + dch * 8;
;     const unsigned dk = ldsb + wid * 1024;
;     ...
;     constexpr int NPW = WIN ? 2 : 4;
;     bf16x8 qfr[4];
;     { const int qrow = seq_base + qw + l31; const bf16_t* qp = QK + ((size_t)((qrow >> 6) * 26 + (qcol >> 6)) * 64 + (qrow & 63)) * 64 + hi * 8;
; #pragma unroll
;       for (int ds = 0; ds < 4; ++ds) qfr[ds] = *(const bf16x8*)(qp + ds * 16); }
;     ...
;     AT_DMA(0); if (NT > 1) AT_DMA(1); if (NT > 2) AT_DMA(2);
;     constexpr float THR = 8.0f;
;     float m_ref = WIN ? sinkp[2 * hsel + half] * LOG2E : 0.f;
;     float l_run = (WIN && hi == 0) ? 1.f : 0.f;
;     float cbase = 0.f;
;     f32x16 cvec;
; #pragma unroll
;     for (int r = 0; r < 16; ++r) cvec[r] = cbase - m_ref;
;     f32x16 o[NDB];
; #pragma unroll
;     for (int db = 0; db < NDB; ++db)
; #pragma unroll
;         for (int r = 0; r < 16; ++r) o[db][r] = 0.f;
;     const int krow = pi32(l31), fK = (krow >> 1) & 7, fV = (l31 >> 1) & 7;
;     int kx[4], vx[4];
; #pragma unroll
;     for (int c = 0; c < 4; ++c) { kx[c] = (WIN ? OFF_K0 : (half ? OFF_K1 : OFF_K0)) + krow * 128 + (((2 * c + hi) ^ fK) << 4); vx[c] = OFF_V + l31 * 128 + (((2 * c + hi) ^ fV) << 4); }
;     const int qabs = qw + l31;
;     const float cfar_lo = __uint_as_float(__builtin_amdgcn_readfirstlane(__float_as_uint(lut[0]))), cfar_hi = __uint_as_float(__builtin_amdgcn_readfirstlane(__float_as_uint(lut[LUTW - 1])));
;     asm volatile("" : "+v"(qfr[0]), "+v"(qfr[1]), "+v"(qfr[2]), "+v"(qfr[3]));
; #pragma clang loop unroll(disable)
;     for (int tr = 0; tr < NT; ++tr) {
;         if (tr + 2 < NT) wait_bar<2 * NPW>(); else if (tr + 1 < NT) wait_bar<NPW>(); else wait_bar<0>();
;         if (tr + 3 < NT) AT_DMA(tr + 3);
;         const int k0 = (t_lo + tr) * 64;
;         const bool skip = WIN && (k0 > qw + 31 + 128 || k0 + 63 < qw - 128);
;         if (!skip) {
;             const bool near = WIN || ((k0 - (qw + 31)) < 128 && (qw - (k0 + 63)) < 128);
;             const float cinit = near ? 0.f : (k0 > qw ? cfar_hi : cfar_lo);
;             if (__builtin_expect(cinit != cbase, 0)) { cbase = cinit; asm volatile("" ::: "memory");
; #pragma unroll
.LBB0_268:
	v_readfirstlane_b32 s33, v230
	s_lshl_b32 s26, s25, 13
	s_bfe_u32 s27, s33, 0x20006
	s_add_i32 s26, s26, s23
	s_lshl_b32 s28, s27, 5
	s_and_b32 s26, s26, 0xfffff800
	s_or_b32 s28, s28, s22
	s_add_i32 s29, s26, 0x10000
	s_lshr_b32 s26, s33, 8
	v_or_b32_e32 v10, s28, v185
	v_or_b32_e32 v170, s29, v10
	s_add_i32 s30, s26, s66
	v_ashrrev_i32_e32 v2, 6, v170
	v_mov_b32_e32 v0, s30
	v_mad_u64_u32 v[2:3], s[30:31], v2, 26, v[0:1]
	v_ashrrev_i32_e32 v3, 31, v2
	v_lshlrev_b64 v[2:3], 13, v[2:3]
	v_lshlrev_b32_e32 v0, 7, v10
	v_lshl_add_u64 v[2:3], s[6:7], 0, v[2:3]
	v_and_b32_e32 v4, 0x1f80, v0
	v_mov_b32_e32 v5, v1
	v_lshl_add_u64 v[2:3], v[2:3], 0, v[4:5]
	v_lshl_add_u64 v[2:3], v[2:3], 0, v[164:165]
	global_load_dwordx4 v[114:117], v[2:3], off offset:96
	global_load_dwordx4 v[118:121], v[2:3], off offset:64
	global_load_dwordx4 v[122:125], v[2:3], off offset:32
	global_load_dwordx4 v[126:129], v[2:3], off
	s_lshr_b32 s62, s33, 6
	s_lshr_b32 s30, s33, 4
	v_lshl_or_b32 v0, s62, 3, v188
	s_and_b32 s30, s30, 4
	s_ashr_i32 s76, s29, 6
	v_bitop3_b32 v4, s30, v186, v189 bitop3:0x36
	v_mad_i64_i32 v[2:3], s[30:31], s76, v194, v[0:1]
	v_lshlrev_b64 v[2:3], 7, v[2:3]
	v_lshl_add_u64 v[2:3], s[6:7], 0, v[2:3]
	v_lshlrev_b32_e32 v4, 4, v4
	s_mul_hi_i32 s31, s76, 0x280
	s_mul_i32 s30, s76, 0x280
	v_lshl_add_u64 v[2:3], v[2:3], 0, v[4:5]
	s_or_b64 s[30:31], s[30:31], s[12:13]
	v_lshl_add_u64 v[2:3], v[2:3], 0, s[18:19]
	v_lshl_add_u64 v[6:7], s[30:31], 0, v[0:1]
	s_lshl_b32 s29, s62, 10
	v_lshlrev_b64 v[6:7], 7, v[6:7]
	v_lshl_add_u64 v[8:9], v[2:3], 0, s[36:37]
	s_add_i32 s29, s29, 0
	s_mov_b32 s30, m0
	s_mov_b32 m0, s29
	s_nop 0
	global_load_lds_dwordx4 v[8:9], off
	s_mov_b32 m0, s30
	v_lshl_add_u64 v[6:7], s[4:5], 0, v[6:7]
	v_lshl_add_u64 v[8:9], v[2:3], 0, s[38:39]
	s_add_i32 s30, s29, 0x2000
	s_mov_b32 s31, m0
	s_mov_b32 m0, s30
	s_nop 0
	global_load_lds_dwordx4 v[8:9], off
	s_mov_b32 m0, s31
	v_lshl_add_u64 v[6:7], v[6:7], 0, v[4:5]
	s_add_i32 s30, s29, 0x4000
	s_mov_b32 s31, m0
	s_mov_b32 m0, s30
	s_nop 0
	global_load_lds_dwordx4 v[6:7], off
	s_mov_b32 m0, s31
	v_lshl_add_u64 v[8:9], v[6:7], 0, s[40:41]
	s_add_i32 s30, s29, 0x6000
	s_mov_b32 s31, m0
	s_mov_b32 m0, s30
	s_nop 0
	global_load_lds_dwordx4 v[8:9], off
	s_mov_b32 m0, s31
	s_add_i32 s30, s29, 0x8000
	v_lshl_add_u64 v[8:9], v[2:3], 0, s[42:43]
	s_mov_b32 s31, m0
	s_mov_b32 m0, s30
	s_nop 0
	global_load_lds_dwordx4 v[8:9], off
	s_mov_b32 m0, s31
	v_lshl_add_u64 v[8:9], v[2:3], 0, s[46:47]
	s_add_i32 s30, s29, 0xa000
	s_mov_b32 s31, m0
	s_mov_b32 m0, s30
	s_nop 0
	global_load_lds_dwordx4 v[8:9], off
	s_mov_b32 m0, s31
	v_lshl_add_u64 v[8:9], v[6:7], 0, s[48:49]
	s_add_i32 s30, s29, 0xc000
	s_mov_b32 s31, m0
	s_mov_b32 m0, s30
	s_nop 0
	global_load_lds_dwordx4 v[8:9], off
	s_mov_b32 m0, s31
	v_lshl_add_u64 v[8:9], v[6:7], 0, s[50:51]
	s_add_i32 s30, s29, 0xe000
	s_mov_b32 s31, m0
	s_mov_b32 m0, s30
	s_nop 0
	global_load_lds_dwordx4 v[8:9], off
	s_mov_b32 m0, s31
	s_add_i32 s30, s29, 0x10000
	v_lshl_add_u64 v[8:9], v[2:3], 0, s[52:53]
	s_mov_b32 s31, m0
	s_mov_b32 m0, s30
	s_nop 0
	global_load_lds_dwordx4 v[8:9], off
	s_mov_b32 m0, s31
	v_lshl_add_u64 v[2:3], v[2:3], 0, s[54:55]
	s_add_i32 s30, s29, 0x12000
	s_mov_b32 s31, m0
	s_mov_b32 m0, s30
	s_nop 0
	global_load_lds_dwordx4 v[2:3], off
	s_mov_b32 m0, s31
	v_lshl_add_u64 v[2:3], v[6:7], 0, s[56:57]
	s_add_i32 s30, s29, 0x14000
	v_lshl_add_u64 v[2:3], v[6:7], 0, s[58:59]
	s_add_i32 s30, s29, 0x16000
	ds_read_b32 v2, v197 offset:14336
	ds_read_b32 v3, v197 offset:16124
	s_cmpk_lt_u32 s33, 0x100
	s_cselect_b64 s[62:63], -1, 0
	s_and_b64 s[30:31], s[62:63], exec
	s_cselect_b32 s30, 0, 0x2000
	v_or_b32_e32 v162, s30, v177
	s_waitcnt lgkmcnt(1)
	v_readfirstlane_b32 s30, v2
	s_waitcnt lgkmcnt(0)
	v_readfirstlane_b32 s31, v3
	v_lshlrev_b64 v[2:3], 7, v[0:1]
	v_mad_i64_i32 v[6:7], s[64:65], s76, v198, v[2:3]
	v_mad_i64_i32 v[2:3], s[64:65], s76, v199, v[2:3]
	v_or_b32_e32 v6, v6, v4
	v_or_b32_e32 v2, v2, v4
	v_lshlrev_b32_e32 v0, 2, v10
	v_mov_b32_e32 v14, v1
	v_mov_b32_e32 v15, v1
	v_lshl_add_u64 v[172:173], s[20:21], 0, v[6:7]
	v_lshl_add_u64 v[174:175], s[16:17], 0, v[2:3]
	v_sub_u32_e32 v171, v195, v0
	v_mov_b32_e32 v0, v1
	v_mov_b32_e32 v2, v1
	v_mov_b32_e32 v3, v1
	v_mov_b32_e32 v4, v1
	v_mov_b32_e32 v6, v1
	v_mov_b32_e32 v7, v1
	v_mov_b32_e32 v8, v1
	v_mov_b32_e32 v9, v1
	v_mov_b32_e32 v10, v1
	v_mov_b32_e32 v11, v1
	v_mov_b32_e32 v12, v1
	v_mov_b32_e32 v13, v1
	v_mov_b64_e32 v[64:65], v[14:15]
	v_mov_b64_e32 v[48:49], v[14:15]
	v_mov_b64_e32 v[32:33], v[14:15]
	v_mov_b64_e32 v[62:63], v[12:13]
	v_mov_b64_e32 v[60:61], v[10:11]
	v_mov_b64_e32 v[58:59], v[8:9]
	v_mov_b64_e32 v[56:57], v[6:7]
	v_mov_b64_e32 v[54:55], v[4:5]
	v_mov_b64_e32 v[52:53], v[2:3]
	v_mov_b64_e32 v[50:51], v[0:1]
	v_mov_b64_e32 v[46:47], v[12:13]
	v_mov_b64_e32 v[44:45], v[10:11]
	v_mov_b64_e32 v[42:43], v[8:9]
	v_mov_b64_e32 v[40:41], v[6:7]
	v_mov_b64_e32 v[38:39], v[4:5]
	v_mov_b64_e32 v[36:37], v[2:3]
	v_mov_b64_e32 v[34:35], v[0:1]
	v_mov_b64_e32 v[30:31], v[12:13]
	v_mov_b64_e32 v[28:29], v[10:11]
	v_mov_b64_e32 v[26:27], v[8:9]
	v_mov_b64_e32 v[24:25], v[6:7]
	v_mov_b64_e32 v[22:23], v[4:5]
	v_mov_b64_e32 v[20:21], v[2:3]
	v_mov_b64_e32 v[18:19], v[0:1]
	v_mov_b64_e32 v[16:17], v[14:15]
	s_add_i32 s33, s28, 0x9f
	s_add_i32 s67, s28, 0xffffff41
	s_mov_b32 s76, 0
	s_mov_b32 s77, 0
	s_mov_b32 s78, 0x10000
	v_mov_b64_e32 v[14:15], v[12:13]
	v_mov_b64_e32 v[12:13], v[10:11]
	v_mov_b64_e32 v[10:11], v[8:9]
	v_mov_b64_e32 v[8:9], v[6:7]
	v_mov_b64_e32 v[6:7], v[4:5]
	v_mov_b64_e32 v[4:5], v[2:3]
	v_mov_b64_e32 v[2:3], v[0:1]
	v_mov_b32_e32 v0, 0
	v_mov_b32_e32 v201, 0
	v_mov_b32_e32 v202, 0
	s_mov_b32 s79, 0
	v_mov_b32_e32 v66, 0
	v_mov_b32_e32 v67, v1
	v_mov_b32_e32 v68, v1
	v_mov_b32_e32 v69, v1
	v_mov_b32_e32 v70, v1
	v_mov_b32_e32 v71, v1
	v_mov_b32_e32 v72, v1
	v_mov_b32_e32 v73, v1
	v_mov_b32_e32 v74, v1
	v_mov_b32_e32 v75, v1
	v_mov_b32_e32 v76, v1
	v_mov_b32_e32 v77, v1
	v_mov_b32_e32 v78, v1
	v_mov_b32_e32 v79, v1
	v_mov_b32_e32 v80, v1
	v_mov_b32_e32 v81, v1
	s_mov_b32 s100, 0
	s_mov_b32 s98, 0xfffec000
	s_mov_b32 s99, -1
	v_lshl_add_u64 v[172:173], v[172:173], 0, s[98:99]
	s_mov_b32 s98, 0xfffcc000
	s_waitcnt vmcnt(10)
	s_cmp_lt_u32 s76, s33
	s_cselect_b64 s[64:65], -1, 0
	s_cmp_gt_i32 s76, s67
	s_cselect_b64 s[80:81], -1, 0
	s_and_b64 s[64:65], s[64:65], s[80:81]
	s_cmp_gt_u32 s76, s28
	s_cselect_b32 s80, s31, s30
	s_cmp_lg_u64 s[64:65], 0
	s_cselect_b32 m0, 0, s80
	s_cmp_lg_u64 s[64:65], 0
	s_cselect_b32 s65, 1, 0
	s_mov_b32 s80, 0
	s_mov_b32 s99, 0x18000
	s_add_i32 s98, s29, 0x18000
	s_add_i32 s101, s29, 0x10000
	v_lshl_add_u64 v[208:209], v[174:175], 0, s[40:41]
	v_lshl_add_u64 v[210:211], v[172:173], 0, s[40:41]
	v_add_u32_e32 v212, v178, v162
	v_add_u32_e32 v213, v180, v162
	v_add_u32_e32 v214, v182, v162
	v_add_u32_e32 v215, v184, v162
	s_branch .LSPs_top
; template <int N> __device__ __forceinline__ void wait_bar() { asm volatile("s_waitcnt vmcnt(%0) lgkmcnt(0)\n\ts_barrier" :: "n"(N) : "memory"); }
; #define AT_DMA(tr) do { const unsigned sb_ = (unsigned)__builtin_amdgcn_readfirstlane(dk + (((tr) & (NSTG - 1)) * STAGE)); const size_t ko_ = (size_t)(tr) * 26 * 4096, vo_ = (size_t)(tr) * 640 * 64; \
;         glds16(kg + ko_, sb_ + OFF_K0); if (!WIN) glds16(kg + ko_ + 4096, sb_ + OFF_K1); glds16(vg + vo_, sb_ + OFF_V); if (!WIN) glds16(vg + vo_ + 64 * 64, sb_ + OFF_V + 8192); } while (0)
; template <bool WIN> ...
;     ...
;         if (tr + 2 < NT) wait_bar<2 * NPW>(); else if (tr + 1 < NT) wait_bar<NPW>(); else wait_bar<0>();
;         if (tr + 3 < NT) AT_DMA(tr + 3);
;         const int k0 = (t_lo + tr) * 64;
;         const bool skip = WIN && (k0 > qw + 31 + 128 || k0 + 63 < qw - 128);
;         if (!skip) {
;             const bool near = WIN || ((k0 - (qw + 31)) < 128 && (qw - (k0 + 63)) < 128);
;             const float cinit = near ? 0.f : (k0 > qw ? cfar_hi : cfar_lo);
;             if (__builtin_expect(cinit != cbase, 0)) { cbase = cinit; asm volatile("" ::: "memory");
; #pragma unroll
;                 for (int r = 0; r < 16; ++r) cvec[r] = cbase - m_ref; }
.LSPs_top:
	s_cmpk_gt_u32 s79, 28
	s_cbranch_scc1 .LSPs_slowtop
	s_waitcnt vmcnt(8) lgkmcnt(0)
	s_barrier
	s_mov_b32 s64, s65
	s_cmp_eq_u32 m0, s100
	s_cbranch_scc0 .LSPs_cin

; #define ALAS __attribute__((address_space(3)))
; template <bool WIN> ...
;     ...
;             bf16x8 va[2 * NDB], vc[2 * NDB];
; #pragma unroll
;             for (int kk = 0; kk < 2; ++kk)
; #pragma unroll
;                 for (int db = 0; db < NDB; ++db) va[kk * NDB + db] = *(const ALAS bf16x8*)(sb + vx[kk] + db * 4096);
;             __builtin_amdgcn_sched_barrier(0);
;             if (near) {
;                 const ALAS float* lb = lut + (k0 + 8 * hi - qabs + LUTC);
; #pragma unroll
;                 for (int r = 0; r < 16; ++r) { s0[r] += lb[16 * (r >> 3) + (r & 7)]; s1[r] += lb[32 + 16 * (r >> 3) + (r & 7)];
;                     if ((r & 7) == 7) __builtin_amdgcn_sched_barrier(0); }
;             }
;     ...
;             float ls0 = 0.f, ls1 = 0.f;
;     ...
;             union PFU { u32x4 u; bf16x8 b; };
;             PFU p0, p1, p2, p3;
;             AT_EXP(s0, 0, p0);
; #pragma unroll
;             for (int kk = 0; kk < 2; ++kk)
; #pragma unroll
;                 for (int db = 0; db < NDB; ++db) vc[kk * NDB + db] = *(const ALAS bf16x8*)(sb + vx[kk + 2] + db * 4096);
;             __builtin_amdgcn_sched_barrier(0);
; #pragma unroll
;             for (int db = 0; db < NDB; ++db) o[db] = __builtin_amdgcn_mfma_f32_32x32x16_bf16(va[db], p0.b, o[db], 0, 0, 0);
;             AT_EXP(s0, 8, p1);
;             __builtin_amdgcn_sched_barrier(0);
; #pragma unroll
;             for (int db = 0; db < NDB; ++db) o[db] = __builtin_amdgcn_mfma_f32_32x32x16_bf16(va[NDB + db], p1.b, o[db], 0, 0, 0);
;             AT_EXP(s1, 0, p2);
;             __builtin_amdgcn_sched_barrier(0);
; #pragma unroll
;             for (int db = 0; db < NDB; ++db) o[db] = __builtin_amdgcn_mfma_f32_32x32x16_bf16(vc[db], p2.b, o[db], 0, 0, 0);
;             AT_EXP(s1, 8, p3);
;             __builtin_amdgcn_sched_barrier(0);
; #pragma unroll
;             for (int db = 0; db < NDB; ++db) o[db] = __builtin_amdgcn_mfma_f32_32x32x16_bf16(vc[NDB + db], p3.b, o[db], 0, 0, 0);
;             __builtin_amdgcn_sched_barrier(0);
;     ...
;             l_run += ls0 + ls1;
.LSPs_vrd:
	v_add3_u32 v236, s99, v179, v187
	ds_read_b128 v[146:149], v236 offset:16384
	ds_read_b128 v[150:153], v236 offset:20480
	ds_read_b128 v[154:157], v236 offset:24576
	ds_read_b128 v[158:161], v236 offset:28672
	v_add3_u32 v237, s99, v181, v187
	ds_read_b128 v[130:133], v237 offset:16384
	ds_read_b128 v[134:137], v237 offset:20480
	ds_read_b128 v[138:141], v237 offset:24576
	ds_read_b128 v[142:145], v237 offset:28672
	s_nop 1
	s_cmp_eq_u32 s64, 0
	s_cbranch_scc1 .LSPs_pv
	v_add_u32_e32 v203, s77, v171
	v_add_u32_e32 v204, 0x23b80, v203
	v_add_u32_e32 v206, 0x23c00, v203
	v_add_u32_e32 v210, 0x23c08, v203
	v_add_u32_e32 v208, 0x23b88, v203
	v_add_u32_e32 v218, 0x23c10, v203
	v_add_u32_e32 v212, 0x23b90, v203
	v_add_u32_e32 v216, 0x23c18, v203
	v_add_u32_e32 v214, 0x23b98, v203
	ds_read2_b32 v[204:205], v204 offset1:1
	ds_read2_b32 v[206:207], v206 offset1:1
	ds_read2_b32 v[208:209], v208 offset1:1
	ds_read2_b32 v[210:211], v210 offset1:1
	ds_read2_b32 v[212:213], v212 offset1:1
	ds_read2_b32 v[214:215], v214 offset1:1
	ds_read2_b32 v[216:217], v216 offset1:1
	ds_read2_b32 v[218:219], v218 offset1:1
	v_add_u32_e32 v220, 0x23bc0, v203
	v_add_u32_e32 v222, 0x23c40, v203
	v_add_u32_e32 v226, 0x23c48, v203
	v_add_u32_e32 v224, 0x23bc8, v203
	v_add_u32_e32 v228, 0x23bd0, v203
	v_add_u32_e32 v234, 0x23c58, v203
	ds_read2_b32 v[220:221], v220 offset1:1
	ds_read2_b32 v[222:223], v222 offset1:1
	ds_read2_b32 v[224:225], v224 offset1:1
	ds_read2_b32 v[226:227], v226 offset1:1
	v_add_u32_e32 v231, 0x23c50, v203
	v_add_u32_e32 v203, 0x23bd8, v203
	ds_read2_b32 v[228:229], v228 offset1:1
	ds_read2_b32 v[232:233], v203 offset1:1
	ds_read2_b32 v[234:235], v234 offset1:1
	ds_read2_b32 v[236:237], v231 offset1:1
	s_waitcnt lgkmcnt(10)
	v_pk_add_f32 v[104:105], v[104:105], v[214:215]
	v_pk_add_f32 v[102:103], v[102:103], v[212:213]
	v_pk_add_f32 v[100:101], v[100:101], v[208:209]
	s_waitcnt lgkmcnt(2)
	v_pk_add_f32 v[112:113], v[112:113], v[232:233]
	v_pk_add_f32 v[110:111], v[110:111], v[228:229]
	v_pk_add_f32 v[108:109], v[108:109], v[224:225]
	v_pk_add_f32 v[106:107], v[106:107], v[220:221]
	v_pk_add_f32 v[98:99], v[98:99], v[204:205]
	v_pk_add_f32 v[88:89], v[88:89], v[216:217]
	v_pk_add_f32 v[86:87], v[86:87], v[218:219]
	v_pk_add_f32 v[84:85], v[84:85], v[210:211]
	s_waitcnt lgkmcnt(1)
	v_pk_add_f32 v[96:97], v[96:97], v[234:235]
	s_waitcnt lgkmcnt(0)
	v_pk_add_f32 v[94:95], v[94:95], v[236:237]
	v_pk_add_f32 v[92:93], v[92:93], v[226:227]
	v_pk_add_f32 v[90:91], v[90:91], v[222:223]
	v_pk_add_f32 v[82:83], v[82:83], v[206:207]
.LSPs_pv:
	s_cmp_eq_u32 s79, 0
	s_cbranch_scc1 .LSPs_pure
	s_waitcnt lgkmcnt(4)
	v_mfma_f32_32x32x16_bf16 v[50:65], v[146:149], v[238:241], v[50:65]
	v_exp_f32_e32 v98, v98
	v_exp_f32_e32 v99, v99
	v_exp_f32_e32 v100, v100
	v_mfma_f32_32x32x16_bf16 v[34:49], v[150:153], v[238:241], v[34:49]
	v_exp_f32_e32 v101, v101
	v_exp_f32_e32 v102, v102
	v_exp_f32_e32 v103, v103
	v_add_f32_e32 v228, v98, v99
	v_mov_b32_e32 v229, v100
	v_mfma_f32_32x32x16_bf16 v[18:33], v[154:157], v[238:241], v[18:33]
	v_exp_f32_e32 v104, v104
	v_exp_f32_e32 v105, v105
	v_exp_f32_e32 v106, v106
	v_add_f32_e32 v228, v228, v101
	v_add_f32_e32 v229, v229, v102
	v_add_f32_e32 v228, v228, v103
	v_mfma_f32_32x32x16_bf16 v[2:17], v[158:161], v[238:241], v[2:17]
	v_exp_f32_e32 v107, v107
	v_exp_f32_e32 v108, v108
	v_exp_f32_e32 v109, v109
	v_add_f32_e32 v229, v229, v104
	v_add_f32_e32 v228, v228, v105
	v_add_f32_e32 v229, v229, v106
	v_add3_u32 v236, s99, v183, v187
	ds_read_b128 v[146:149], v236 offset:16384
	ds_read_b128 v[150:153], v236 offset:20480
	ds_read_b128 v[154:157], v236 offset:24576
	ds_read_b128 v[158:161], v236 offset:28672
	s_waitcnt lgkmcnt(4)
	v_mfma_f32_32x32x16_bf16 v[50:65], v[130:133], v[242:245], v[50:65]
	v_exp_f32_e32 v110, v110
	v_exp_f32_e32 v111, v111
	v_exp_f32_e32 v112, v112
	v_add_f32_e32 v228, v228, v107
	v_add_f32_e32 v229, v229, v108
	v_add_f32_e32 v228, v228, v109
	v_cvt_pk_bf16_f32 v238, v98, v99
	v_lshl_add_u64 v[174:175], v[174:175], 0, s[60:61]
	v_lshl_add_u64 v[172:173], v[172:173], 0, s[48:49]
	s_add_i32 s98, s78, 0x10000
	v_mfma_f32_32x32x16_bf16 v[34:49], v[134:137], v[242:245], v[34:49]
	v_exp_f32_e32 v113, v113
	v_exp_f32_e32 v82, v82
	v_exp_f32_e32 v83, v83
	v_add_f32_e32 v229, v229, v110
	v_add_f32_e32 v228, v228, v111
	v_add_f32_e32 v229, v229, v112
	v_cvt_pk_bf16_f32 v239, v100, v101
	s_and_b32 s98, s98, 0x18000
	s_add_i32 s98, s98, s29
	s_add_i32 s101, s78, 0x8000
	v_mfma_f32_32x32x16_bf16 v[18:33], v[138:141], v[242:245], v[18:33]
	v_exp_f32_e32 v84, v84
	v_exp_f32_e32 v85, v85
	v_exp_f32_e32 v86, v86
	v_add_f32_e32 v228, v228, v113
	v_add_f32_e32 v229, v229, v82
	v_add_f32_e32 v228, v228, v83
	v_cvt_pk_bf16_f32 v240, v102, v103
	s_and_b32 s101, s101, 0x18000
	s_add_i32 s101, s101, s29
	v_lshl_add_u64 v[208:209], v[174:175], 0, s[40:41]
	v_mfma_f32_32x32x16_bf16 v[2:17], v[142:145], v[242:245], v[2:17]
	v_exp_f32_e32 v87, v87
	v_exp_f32_e32 v88, v88
	v_exp_f32_e32 v89, v89
	v_add_f32_e32 v229, v229, v84
	v_add_f32_e32 v228, v228, v85
	v_add_f32_e32 v229, v229, v86
	v_cvt_pk_bf16_f32 v241, v104, v105
	v_lshl_add_u64 v[210:211], v[172:173], 0, s[40:41]
	s_add_i32 s80, s78, 0xffff8000
	s_and_b32 s80, s80, 0x18000
	v_add3_u32 v237, s99, v190, v187
	ds_read_b128 v[130:133], v237 offset:16384
	ds_read_b128 v[134:137], v237 offset:20480
	ds_read_b128 v[138:141], v237 offset:24576
	ds_read_b128 v[142:145], v237 offset:28672
	s_waitcnt lgkmcnt(4)
; #define ALAS __attribute__((address_space(3)))
; template <bool WIN> ...
;     ...
;         const int k0 = (t_lo + tr) * 64;
;         const bool skip = WIN && (k0 > qw + 31 + 128 || k0 + 63 < qw - 128);
;         if (!skip) {
;             const bool near = WIN || ((k0 - (qw + 31)) < 128 && (qw - (k0 + 63)) < 128);
;             const float cinit = near ? 0.f : (k0 > qw ? cfar_hi : cfar_lo);
;             if (__builtin_expect(cinit != cbase, 0)) { cbase = cinit; asm volatile("" ::: "memory");
; #pragma unroll
;                 for (int r = 0; r < 16; ++r) cvec[r] = cbase - m_ref; }
;     ...
;             float ls0 = 0.f, ls1 = 0.f;
;     ...
;             union PFU { u32x4 u; bf16x8 b; };
;             PFU p0, p1, p2, p3;
;             AT_EXP(s0, 0, p0);
; #pragma unroll
;             for (int kk = 0; kk < 2; ++kk)
; #pragma unroll
;                 for (int db = 0; db < NDB; ++db) vc[kk * NDB + db] = *(const ALAS bf16x8*)(sb + vx[kk + 2] + db * 4096);
;             __builtin_amdgcn_sched_barrier(0);
; #pragma unroll
;             for (int db = 0; db < NDB; ++db) o[db] = __builtin_amdgcn_mfma_f32_32x32x16_bf16(va[db], p0.b, o[db], 0, 0, 0);
;             AT_EXP(s0, 8, p1);
;             __builtin_amdgcn_sched_barrier(0);
; #pragma unroll
;             for (int db = 0; db < NDB; ++db) o[db] = __builtin_amdgcn_mfma_f32_32x32x16_bf16(va[NDB + db], p1.b, o[db], 0, 0, 0);
;             AT_EXP(s1, 0, p2);
;             __builtin_amdgcn_sched_barrier(0);
; #pragma unroll
;             for (int db = 0; db < NDB; ++db) o[db] = __builtin_amdgcn_mfma_f32_32x32x16_bf16(vc[db], p2.b, o[db], 0, 0, 0);
;             AT_EXP(s1, 8, p3);
;             __builtin_amdgcn_sched_barrier(0);
; #pragma unroll
;             for (int db = 0; db < NDB; ++db) o[db] = __builtin_amdgcn_mfma_f32_32x32x16_bf16(vc[NDB + db], p3.b, o[db], 0, 0, 0);
;             __builtin_amdgcn_sched_barrier(0);
;     ...
;             l_run += ls0 + ls1;
	v_mfma_f32_32x32x16_bf16 v[50:65], v[146:149], v[246:249], v[50:65]
	v_exp_f32_e32 v90, v90
	v_exp_f32_e32 v91, v91
	v_exp_f32_e32 v92, v92
	v_add_f32_e32 v228, v228, v87
	v_add_f32_e32 v229, v229, v88
	v_add_f32_e32 v228, v228, v89
	v_cvt_pk_bf16_f32 v242, v106, v107
	v_add3_u32 v212, s80, v178, v162
	v_add3_u32 v213, s80, v180, v162
	v_add3_u32 v214, s80, v182, v162
	v_mfma_f32_32x32x16_bf16 v[34:49], v[150:153], v[246:249], v[34:49]
	v_exp_f32_e32 v93, v93
	v_exp_f32_e32 v94, v94
	v_exp_f32_e32 v95, v95
	v_add_f32_e32 v229, v229, v90
	v_add_f32_e32 v228, v228, v91
	v_add_f32_e32 v229, v229, v92
	v_cvt_pk_bf16_f32 v243, v108, v109
	v_add3_u32 v215, s80, v184, v162
	s_add_i32 s99, s76, 64
	s_cmp_gt_u32 s99, s28
	v_mfma_f32_32x32x16_bf16 v[18:33], v[154:157], v[246:249], v[18:33]
	v_exp_f32_e32 v96, v96
	v_exp_f32_e32 v97, v97
	v_add_f32_e32 v228, v228, v93
	v_add_f32_e32 v229, v229, v94
	v_add_f32_e32 v228, v228, v95
	v_cvt_pk_bf16_f32 v244, v110, v111
	s_cselect_b32 m0, s31, s30
	s_cmp_lt_u32 s99, s33
	s_cselect_b32 s65, 1, 0
	v_mfma_f32_32x32x16_bf16 v[2:17], v[158:161], v[246:249], v[2:17]
	v_add_f32_e32 v229, v229, v96
	v_add_f32_e32 v228, v228, v97
	v_cvt_pk_bf16_f32 v245, v112, v113
	s_cmp_gt_i32 s99, s67
	s_cselect_b32 s65, s65, 0
	s_cmp_lg_u32 s65, 0
	s_waitcnt lgkmcnt(0)
	v_mfma_f32_32x32x16_bf16 v[50:65], v[130:133], v[250:253], v[50:65]
	v_cvt_pk_bf16_f32 v246, v82, v83
	s_cselect_b32 m0, 0, m0
	s_add_i32 s99, s78, 0xffff0000
	s_and_b32 s99, s99, 0x18000
	v_mfma_f32_32x32x16_bf16 v[34:49], v[134:137], v[250:253], v[34:49]
	v_cvt_pk_bf16_f32 v247, v84, v85
	v_mfma_f32_32x32x16_bf16 v[18:33], v[138:141], v[250:253], v[18:33]
	v_cvt_pk_bf16_f32 v248, v86, v87
	v_mfma_f32_32x32x16_bf16 v[2:17], v[142:145], v[250:253], v[2:17]
	v_cvt_pk_bf16_f32 v249, v88, v89
	v_cvt_pk_bf16_f32 v250, v90, v91
	v_cvt_pk_bf16_f32 v251, v92, v93
	v_cvt_pk_bf16_f32 v252, v94, v95
	v_cvt_pk_bf16_f32 v253, v96, v97
	v_add_f32_e32 v228, v228, v229
	v_cmp_nge_f32_e32 vcc, 0x53800000, v228
	s_cbranch_vccnz .LSPs_redo
	s_add_i32 s79, s79, 1
	s_add_i32 s78, s78, 0x8000
	s_addk_i32 s77, 0x100
	s_add_i32 s76, s76, 64
	v_add_f32_e32 v0, v0, v228
	s_cmpk_eq_i32 s77, 0x2000
	s_cbranch_scc0 .LSPs_top
	s_branch .LSPs_exit
.LSPs_pure:
	v_lshl_add_u64 v[174:175], v[174:175], 0, s[60:61]
	v_lshl_add_u64 v[172:173], v[172:173], 0, s[48:49]
	s_add_i32 s98, s78, 0x10000
	s_and_b32 s98, s98, 0x18000
	s_add_i32 s98, s98, s29
	s_add_i32 s101, s78, 0x8000
	s_and_b32 s101, s101, 0x18000
	s_add_i32 s101, s101, s29
	v_lshl_add_u64 v[208:209], v[174:175], 0, s[40:41]
	v_lshl_add_u64 v[210:211], v[172:173], 0, s[40:41]
	s_add_i32 s80, s78, 0xffff8000
	s_and_b32 s80, s80, 0x18000
	v_add3_u32 v212, s80, v178, v162
	v_add3_u32 v213, s80, v180, v162
	v_add3_u32 v214, s80, v182, v162
	v_add3_u32 v215, s80, v184, v162
	s_add_i32 s99, s76, 64
	s_cmp_gt_u32 s99, s28
	s_cselect_b32 m0, s31, s30
	s_cmp_lt_u32 s99, s33
	s_cselect_b32 s65, 1, 0
	s_cmp_gt_i32 s99, s67
	s_cselect_b32 s65, s65, 0
	s_cmp_lg_u32 s65, 0
	s_cselect_b32 m0, 0, m0
	s_add_i32 s99, s78, 0xffff0000
	s_and_b32 s99, s99, 0x18000
	v_exp_f32_e32 v98, v98
	v_exp_f32_e32 v99, v99
	v_exp_f32_e32 v100, v100
	v_exp_f32_e32 v101, v101
	v_exp_f32_e32 v102, v102
	v_exp_f32_e32 v103, v103
	v_exp_f32_e32 v104, v104
	v_exp_f32_e32 v105, v105
	v_cvt_pk_bf16_f32 v238, v98, v99
	v_cvt_pk_bf16_f32 v239, v100, v101
	v_cvt_pk_bf16_f32 v240, v102, v103
	v_cvt_pk_bf16_f32 v241, v104, v105
	v_mov_b32_e32 v228, v98
	v_mov_b32_e32 v229, v102
	v_add_f32_e32 v228, v228, v99
	v_add_f32_e32 v229, v229, v103
	v_add_f32_e32 v228, v228, v100
	v_add_f32_e32 v229, v229, v104
	v_add_f32_e32 v228, v228, v101
	v_add_f32_e32 v229, v229, v105
	v_exp_f32_e32 v106, v106
	v_exp_f32_e32 v107, v107
	v_exp_f32_e32 v108, v108
	v_exp_f32_e32 v109, v109
	v_exp_f32_e32 v110, v110
	v_exp_f32_e32 v111, v111
	v_exp_f32_e32 v112, v112
	v_exp_f32_e32 v113, v113
	v_cvt_pk_bf16_f32 v242, v106, v107
	v_cvt_pk_bf16_f32 v243, v108, v109
	v_cvt_pk_bf16_f32 v244, v110, v111
	v_cvt_pk_bf16_f32 v245, v112, v113
	v_add_f32_e32 v228, v228, v106
	v_add_f32_e32 v229, v229, v110
	v_add_f32_e32 v228, v228, v107
	v_add_f32_e32 v229, v229, v111
	v_add_f32_e32 v228, v228, v108
	v_add_f32_e32 v229, v229, v112
	v_add_f32_e32 v228, v228, v109
	v_add_f32_e32 v229, v229, v113
	v_exp_f32_e32 v82, v82
	v_exp_f32_e32 v83, v83
	v_exp_f32_e32 v84, v84
	v_exp_f32_e32 v85, v85
	v_exp_f32_e32 v86, v86
	v_exp_f32_e32 v87, v87
	v_exp_f32_e32 v88, v88
	v_exp_f32_e32 v89, v89
	v_cvt_pk_bf16_f32 v246, v82, v83
	v_cvt_pk_bf16_f32 v247, v84, v85
	v_cvt_pk_bf16_f32 v248, v86, v87
	v_cvt_pk_bf16_f32 v249, v88, v89
	v_add_f32_e32 v228, v228, v82
	v_add_f32_e32 v229, v229, v86
	v_add_f32_e32 v228, v228, v83
	v_add_f32_e32 v229, v229, v87
	v_add_f32_e32 v228, v228, v84
	v_add_f32_e32 v229, v229, v88
	v_add_f32_e32 v228, v228, v85
	v_add_f32_e32 v229, v229, v89
	v_exp_f32_e32 v90, v90
	v_exp_f32_e32 v91, v91
	v_exp_f32_e32 v92, v92
	v_exp_f32_e32 v93, v93
	v_exp_f32_e32 v94, v94
	v_exp_f32_e32 v95, v95
	v_exp_f32_e32 v96, v96
	v_exp_f32_e32 v97, v97
	v_cvt_pk_bf16_f32 v250, v90, v91
	v_cvt_pk_bf16_f32 v251, v92, v93
	v_cvt_pk_bf16_f32 v252, v94, v95
	v_cvt_pk_bf16_f32 v253, v96, v97
	v_add_f32_e32 v228, v228, v90
	v_add_f32_e32 v229, v229, v94
	v_add_f32_e32 v228, v228, v91
	v_add_f32_e32 v229, v229, v95
	v_add_f32_e32 v228, v228, v92
	v_add_f32_e32 v229, v229, v96
	v_add_f32_e32 v228, v228, v93
	v_add_f32_e32 v229, v229, v97
	v_add_f32_e32 v228, v228, v229
	v_cmp_nge_f32_e32 vcc, 0x53800000, v228
	s_cbranch_vccnz .LSPs_redo
	s_add_i32 s79, s79, 1
	s_add_i32 s78, s78, 0x8000
	s_addk_i32 s77, 0x100
	s_add_i32 s76, s76, 64
	v_add_f32_e32 v0, v0, v228
	s_cmpk_eq_i32 s77, 0x2000
	s_cbranch_scc0 .LSPs_top
	s_branch .LSPs_exit
; #define ALAS __attribute__((address_space(3)))
; template <bool WIN> ...
;     ...
;             const ALAS unsigned char* sb = lds + (tr & (NSTG - 1)) * STAGE;
;             {
;                 bf16x8 ka[8];
; #pragma unroll
;                 for (int ds = 0; ds < 4; ++ds) { ka[2 * ds] = *(const ALAS bf16x8*)(sb + kx[ds]); ka[2 * ds + 1] = *(const ALAS bf16x8*)(sb + kx[ds] + 4096); }
;                 __builtin_amdgcn_sched_barrier(0);
;                 s0 = __builtin_amdgcn_mfma_f32_32x32x16_bf16(ka[0], qf(0), cvec, 0, 0, 0);
;                 s1 = __builtin_amdgcn_mfma_f32_32x32x16_bf16(ka[1], qf(0), cvec, 0, 0, 0);
; #pragma unroll
;                 for (int ds = 1; ds < 4; ++ds) {
;                     s0 = __builtin_amdgcn_mfma_f32_32x32x16_bf16(ka[2 * ds], qf(ds), s0, 0, 0, 0);
;                     s1 = __builtin_amdgcn_mfma_f32_32x32x16_bf16(ka[2 * ds + 1], qf(ds), s1, 0, 0, 0);
;                 }
;             }
;             bf16x8 va[2 * NDB], vc[2 * NDB];
; #pragma unroll
;             for (int kk = 0; kk < 2; ++kk)
; #pragma unroll
;                 for (int db = 0; db < NDB; ++db) va[kk * NDB + db] = *(const ALAS bf16x8*)(sb + vx[kk] + db * 4096);
;             __builtin_amdgcn_sched_barrier(0);
;             if (near) {
;                 const ALAS float* lb = lut + (k0 + 8 * hi - qabs + LUTC);
; #pragma unroll
;                 for (int r = 0; r < 16; ++r) { s0[r] += lb[16 * (r >> 3) + (r & 7)]; s1[r] += lb[32 + 16 * (r >> 3) + (r & 7)];
;                     if ((r & 7) == 7) __builtin_amdgcn_sched_barrier(0); }
;             }
.LSPs_redo:
	s_add_i32 s80, s78, 0xffff0000
	s_and_b32 s80, s80, 0x18000
	v_add3_u32 v203, s80, v178, v162
	ds_read_b128 v[130:133], v203
	ds_read_b128 v[134:137], v203 offset:4096
	v_add3_u32 v203, s80, v180, v162
	ds_read_b128 v[138:141], v203
	ds_read_b128 v[142:145], v203 offset:4096
	v_add3_u32 v203, s80, v182, v162
	ds_read_b128 v[146:149], v203
	ds_read_b128 v[150:153], v203 offset:4096
	v_add3_u32 v203, s80, v184, v162
	ds_read_b128 v[158:161], v203
	ds_read_b128 v[204:207], v203 offset:4096
	s_waitcnt lgkmcnt(0)
	v_mfma_f32_32x32x16_bf16 v[98:113], v[130:133], v[126:129], v[66:81]
	v_mfma_f32_32x32x16_bf16 v[82:97], v[134:137], v[126:129], v[66:81]
	v_mfma_f32_32x32x16_bf16 v[98:113], v[138:141], v[122:125], v[98:113]
	v_mfma_f32_32x32x16_bf16 v[82:97], v[142:145], v[122:125], v[82:97]
	v_mfma_f32_32x32x16_bf16 v[98:113], v[146:149], v[118:121], v[98:113]
	v_mfma_f32_32x32x16_bf16 v[82:97], v[150:153], v[118:121], v[82:97]
	v_mfma_f32_32x32x16_bf16 v[98:113], v[158:161], v[114:117], v[98:113]
	v_mfma_f32_32x32x16_bf16 v[82:97], v[204:207], v[114:117], v[82:97]
	s_nop 7
	s_nop 7
	s_cmp_eq_u32 s64, 0
	s_cbranch_scc1 .LSPs_redomax
	v_add_u32_e32 v203, s77, v171
	v_add_u32_e32 v204, 0x23b80, v203
	v_add_u32_e32 v206, 0x23c00, v203
	v_add_u32_e32 v210, 0x23c08, v203
	v_add_u32_e32 v208, 0x23b88, v203
	v_add_u32_e32 v218, 0x23c10, v203
	v_add_u32_e32 v212, 0x23b90, v203
	v_add_u32_e32 v216, 0x23c18, v203
	v_add_u32_e32 v214, 0x23b98, v203
	ds_read2_b32 v[204:205], v204 offset1:1
	ds_read2_b32 v[206:207], v206 offset1:1
	ds_read2_b32 v[208:209], v208 offset1:1
	ds_read2_b32 v[210:211], v210 offset1:1
	ds_read2_b32 v[212:213], v212 offset1:1
	ds_read2_b32 v[214:215], v214 offset1:1
	ds_read2_b32 v[216:217], v216 offset1:1
	ds_read2_b32 v[218:219], v218 offset1:1
	v_add_u32_e32 v220, 0x23bc0, v203
	v_add_u32_e32 v222, 0x23c40, v203
	v_add_u32_e32 v226, 0x23c48, v203
	v_add_u32_e32 v224, 0x23bc8, v203
	v_add_u32_e32 v228, 0x23bd0, v203
	v_add_u32_e32 v234, 0x23c58, v203
	ds_read2_b32 v[220:221], v220 offset1:1
	ds_read2_b32 v[222:223], v222 offset1:1
	ds_read2_b32 v[224:225], v224 offset1:1
	ds_read2_b32 v[226:227], v226 offset1:1
	v_add_u32_e32 v231, 0x23c50, v203
	v_add_u32_e32 v203, 0x23bd8, v203
	ds_read2_b32 v[228:229], v228 offset1:1
	ds_read2_b32 v[232:233], v203 offset1:1
	ds_read2_b32 v[234:235], v234 offset1:1
	ds_read2_b32 v[236:237], v231 offset1:1
	s_waitcnt lgkmcnt(10)
	v_pk_add_f32 v[104:105], v[104:105], v[214:215]
	v_pk_add_f32 v[102:103], v[102:103], v[212:213]
	v_pk_add_f32 v[100:101], v[100:101], v[208:209]
	s_waitcnt lgkmcnt(2)
	v_pk_add_f32 v[112:113], v[112:113], v[232:233]
	v_pk_add_f32 v[110:111], v[110:111], v[228:229]
	v_pk_add_f32 v[108:109], v[108:109], v[224:225]
	v_pk_add_f32 v[106:107], v[106:107], v[220:221]
	v_pk_add_f32 v[98:99], v[98:99], v[204:205]
	v_pk_add_f32 v[88:89], v[88:89], v[216:217]
	v_pk_add_f32 v[86:87], v[86:87], v[218:219]
	v_pk_add_f32 v[84:85], v[84:85], v[210:211]
	s_waitcnt lgkmcnt(1)
	v_pk_add_f32 v[96:97], v[96:97], v[234:235]
	s_waitcnt lgkmcnt(0)
	v_pk_add_f32 v[94:95], v[94:95], v[236:237]
	v_pk_add_f32 v[92:93], v[92:93], v[226:227]
	v_pk_add_f32 v[90:91], v[90:91], v[222:223]
	v_pk_add_f32 v[82:83], v[82:83], v[206:207]

; #define ALAS __attribute__((address_space(3)))
; template <int N> __device__ __forceinline__ void wait_bar() { asm volatile("s_waitcnt vmcnt(%0) lgkmcnt(0)\n\ts_barrier" :: "n"(N) : "memory"); }
; #define AT_DMA(tr) do { const unsigned sb_ = (unsigned)__builtin_amdgcn_readfirstlane(dk + (((tr) & (NSTG - 1)) * STAGE)); const size_t ko_ = (size_t)(tr) * 26 * 4096, vo_ = (size_t)(tr) * 640 * 64; \
;         glds16(kg + ko_, sb_ + OFF_K0); if (!WIN) glds16(kg + ko_ + 4096, sb_ + OFF_K1); glds16(vg + vo_, sb_ + OFF_V); if (!WIN) glds16(vg + vo_ + 64 * 64, sb_ + OFF_V + 8192); } while (0)
; template <bool WIN> ...
;     ...
;         if (tr + 2 < NT) wait_bar<2 * NPW>(); else if (tr + 1 < NT) wait_bar<NPW>(); else wait_bar<0>();
;         if (tr + 3 < NT) AT_DMA(tr + 3);
;     ...
;             float ls0 = 0.f, ls1 = 0.f;
;     ...
;             union PFU { u32x4 u; bf16x8 b; };
;             PFU p0, p1, p2, p3;
;             AT_EXP(s0, 0, p0);
; #pragma unroll
;             for (int kk = 0; kk < 2; ++kk)
; #pragma unroll
;                 for (int db = 0; db < NDB; ++db) vc[kk * NDB + db] = *(const ALAS bf16x8*)(sb + vx[kk + 2] + db * 4096);
;             __builtin_amdgcn_sched_barrier(0);
; #pragma unroll
;             for (int db = 0; db < NDB; ++db) o[db] = __builtin_amdgcn_mfma_f32_32x32x16_bf16(va[db], p0.b, o[db], 0, 0, 0);
;             AT_EXP(s0, 8, p1);
;             __builtin_amdgcn_sched_barrier(0);
; #pragma unroll
;             for (int db = 0; db < NDB; ++db) o[db] = __builtin_amdgcn_mfma_f32_32x32x16_bf16(va[NDB + db], p1.b, o[db], 0, 0, 0);
;             AT_EXP(s1, 0, p2);
;             __builtin_amdgcn_sched_barrier(0);
; #pragma unroll
;             for (int db = 0; db < NDB; ++db) o[db] = __builtin_amdgcn_mfma_f32_32x32x16_bf16(vc[db], p2.b, o[db], 0, 0, 0);
;             AT_EXP(s1, 8, p3);
;             __builtin_amdgcn_sched_barrier(0);
; #pragma unroll
;             for (int db = 0; db < NDB; ++db) o[db] = __builtin_amdgcn_mfma_f32_32x32x16_bf16(vc[NDB + db], p3.b, o[db], 0, 0, 0);
;             __builtin_amdgcn_sched_barrier(0);
;     ...
;             l_run += ls0 + ls1;
;         }
.LSPs_pure2:
	s_add_i32 s80, s78, 0xffff8000
	s_and_b32 s80, s80, 0x18000
	v_lshl_add_u64 v[208:209], v[174:175], 0, s[40:41]
	v_lshl_add_u64 v[210:211], v[172:173], 0, s[40:41]
	v_add3_u32 v212, s80, v178, v162
	v_add3_u32 v213, s80, v180, v162
	v_add3_u32 v214, s80, v182, v162
	v_add3_u32 v215, s80, v184, v162
	v_exp_f32_e32 v98, v98
	v_exp_f32_e32 v99, v99
	v_exp_f32_e32 v100, v100
	v_exp_f32_e32 v101, v101
	v_exp_f32_e32 v102, v102
	v_exp_f32_e32 v103, v103
	v_exp_f32_e32 v104, v104
	v_exp_f32_e32 v105, v105
	v_cvt_pk_bf16_f32 v238, v98, v99
	v_cvt_pk_bf16_f32 v239, v100, v101
	v_cvt_pk_bf16_f32 v240, v102, v103
	v_cvt_pk_bf16_f32 v241, v104, v105
	v_mov_b32_e32 v228, v98
	v_mov_b32_e32 v229, v102
	v_add_f32_e32 v228, v228, v99
	v_add_f32_e32 v229, v229, v103
	v_add_f32_e32 v228, v228, v100
	v_add_f32_e32 v229, v229, v104
	v_add_f32_e32 v228, v228, v101
	v_add_f32_e32 v229, v229, v105
	v_exp_f32_e32 v106, v106
	v_exp_f32_e32 v107, v107
	v_exp_f32_e32 v108, v108
	v_exp_f32_e32 v109, v109
	v_exp_f32_e32 v110, v110
	v_exp_f32_e32 v111, v111
	v_exp_f32_e32 v112, v112
	v_exp_f32_e32 v113, v113
	v_cvt_pk_bf16_f32 v242, v106, v107
	v_cvt_pk_bf16_f32 v243, v108, v109
	v_cvt_pk_bf16_f32 v244, v110, v111
	v_cvt_pk_bf16_f32 v245, v112, v113
	v_add_f32_e32 v228, v228, v106
	v_add_f32_e32 v229, v229, v110
	v_add_f32_e32 v228, v228, v107
	v_add_f32_e32 v229, v229, v111
	v_add_f32_e32 v228, v228, v108
	v_add_f32_e32 v229, v229, v112
	v_add_f32_e32 v228, v228, v109
	v_add_f32_e32 v229, v229, v113
	v_exp_f32_e32 v82, v82
	v_exp_f32_e32 v83, v83
	v_exp_f32_e32 v84, v84
	v_exp_f32_e32 v85, v85
	v_exp_f32_e32 v86, v86
	v_exp_f32_e32 v87, v87
	v_exp_f32_e32 v88, v88
	v_exp_f32_e32 v89, v89
	v_cvt_pk_bf16_f32 v246, v82, v83
	v_cvt_pk_bf16_f32 v247, v84, v85
	v_cvt_pk_bf16_f32 v248, v86, v87
	v_cvt_pk_bf16_f32 v249, v88, v89
	v_add_f32_e32 v228, v228, v82
	v_add_f32_e32 v229, v229, v86
	v_add_f32_e32 v228, v228, v83
	v_add_f32_e32 v229, v229, v87
	v_add_f32_e32 v228, v228, v84
	v_add_f32_e32 v229, v229, v88
	v_add_f32_e32 v228, v228, v85
	v_add_f32_e32 v229, v229, v89
	v_exp_f32_e32 v90, v90
	v_exp_f32_e32 v91, v91
	v_exp_f32_e32 v92, v92
	v_exp_f32_e32 v93, v93
	v_exp_f32_e32 v94, v94
	v_exp_f32_e32 v95, v95
	v_exp_f32_e32 v96, v96
	v_exp_f32_e32 v97, v97
	v_cvt_pk_bf16_f32 v250, v90, v91
	v_cvt_pk_bf16_f32 v251, v92, v93
	v_cvt_pk_bf16_f32 v252, v94, v95
	v_cvt_pk_bf16_f32 v253, v96, v97
	v_add_f32_e32 v228, v228, v90
	v_add_f32_e32 v229, v229, v94
	v_add_f32_e32 v228, v228, v91
	v_add_f32_e32 v229, v229, v95
	v_add_f32_e32 v228, v228, v92
	v_add_f32_e32 v229, v229, v96
	v_add_f32_e32 v228, v228, v93
	v_add_f32_e32 v229, v229, v97
	v_add_f32_e32 v228, v228, v229
	s_add_i32 s79, s79, 1
	s_add_i32 s78, s78, 0x8000
	s_addk_i32 s77, 0x100
	s_add_i32 s76, s76, 64
	v_add_f32_e32 v0, v0, v228
	s_cmpk_eq_i32 s77, 0x2000
	s_cbranch_scc0 .LSPs_top
	s_branch .LSPs_exit
.LSPs_exit:
	s_add_i32 s99, s78, 0xfffe8000
	s_and_b32 s99, s99, 0x18000
	v_add3_u32 v236, s99, v179, v187
	ds_read_b128 v[146:149], v236 offset:16384
	ds_read_b128 v[150:153], v236 offset:20480
	ds_read_b128 v[154:157], v236 offset:24576
	ds_read_b128 v[158:161], v236 offset:28672
	v_add3_u32 v237, s99, v181, v187
	ds_read_b128 v[130:133], v237 offset:16384
	ds_read_b128 v[134:137], v237 offset:20480
	ds_read_b128 v[138:141], v237 offset:24576
	ds_read_b128 v[142:145], v237 offset:28672
	s_waitcnt lgkmcnt(4)
	v_mfma_f32_32x32x16_bf16 v[50:65], v[146:149], v[238:241], v[50:65]
	v_mfma_f32_32x32x16_bf16 v[34:49], v[150:153], v[238:241], v[34:49]
	v_mfma_f32_32x32x16_bf16 v[18:33], v[154:157], v[238:241], v[18:33]
	v_mfma_f32_32x32x16_bf16 v[2:17], v[158:161], v[238:241], v[2:17]
	v_add3_u32 v236, s99, v183, v187
	ds_read_b128 v[146:149], v236 offset:16384
	ds_read_b128 v[150:153], v236 offset:20480
	ds_read_b128 v[154:157], v236 offset:24576
	ds_read_b128 v[158:161], v236 offset:28672
	s_waitcnt lgkmcnt(4)
	v_mfma_f32_32x32x16_bf16 v[50:65], v[130:133], v[242:245], v[50:65]
	v_mfma_f32_32x32x16_bf16 v[34:49], v[134:137], v[242:245], v[34:49]
	v_mfma_f32_32x32x16_bf16 v[18:33], v[138:141], v[242:245], v[18:33]
	v_mfma_f32_32x32x16_bf16 v[2:17], v[142:145], v[242:245], v[2:17]
	v_add3_u32 v237, s99, v190, v187
	ds_read_b128 v[130:133], v237 offset:16384
	ds_read_b128 v[134:137], v237 offset:20480
	ds_read_b128 v[138:141], v237 offset:24576
	ds_read_b128 v[142:145], v237 offset:28672
	s_waitcnt lgkmcnt(4)
	v_mfma_f32_32x32x16_bf16 v[50:65], v[146:149], v[246:249], v[50:65]
	v_mfma_f32_32x32x16_bf16 v[34:49], v[150:153], v[246:249], v[34:49]
	v_mfma_f32_32x32x16_bf16 v[18:33], v[154:157], v[246:249], v[18:33]
	v_mfma_f32_32x32x16_bf16 v[2:17], v[158:161], v[246:249], v[2:17]
	s_waitcnt lgkmcnt(0)
	v_mfma_f32_32x32x16_bf16 v[50:65], v[130:133], v[250:253], v[50:65]
	v_mfma_f32_32x32x16_bf16 v[34:49], v[134:137], v[250:253], v[34:49]
	v_mfma_f32_32x32x16_bf16 v[18:33], v[138:141], v[250:253], v[18:33]
	v_mfma_f32_32x32x16_bf16 v[2:17], v[142:145], v[250:253], v[2:17]
	s_branch .LBB0_286
.LSPs_slowtop:
	s_cmpk_gt_u32 s79, 29
	s_cbranch_scc1 .LSPs_t0
	s_waitcnt vmcnt(8) lgkmcnt(0)
	s_barrier

; template <bool WIN> ...
;     ...
;             const float cinit = near ? 0.f : (k0 > qw ? cfar_hi : cfar_lo);
;             if (__builtin_expect(cinit != cbase, 0)) { cbase = cinit; asm volatile("" ::: "memory");
; #pragma unroll
;                 for (int r = 0; r < 16; ++r) cvec[r] = cbase - m_ref; }
.LSPs_cin:
	v_mov_b32_e32 v98, m0
	s_mov_b32 s100, m0
	v_sub_f32_e32 v82, v98, v201
	v_mov_b32_e32 v202, v98
	v_mov_b32_e32 v66, v82
	v_mov_b32_e32 v67, v82
	v_mov_b32_e32 v68, v82
	v_mov_b32_e32 v69, v82
	v_mov_b32_e32 v70, v82
	v_mov_b32_e32 v71, v82
	v_mov_b32_e32 v72, v82
	v_mov_b32_e32 v73, v82
	v_mov_b32_e32 v74, v82
	v_mov_b32_e32 v75, v82
	v_mov_b32_e32 v76, v82
	v_mov_b32_e32 v77, v82
	v_mov_b32_e32 v78, v82
	v_mov_b32_e32 v79, v82
	v_mov_b32_e32 v80, v82
	v_mov_b32_e32 v81, v82
	s_branch .LSPs_qk
.LSPs_cin2:
	v_mov_b32_e32 v98, m0
	s_mov_b32 s100, m0
	v_sub_f32_e32 v82, v98, v201
	v_mov_b32_e32 v202, v98
	v_mov_b32_e32 v66, v82
	v_mov_b32_e32 v67, v82
	v_mov_b32_e32 v68, v82
	v_mov_b32_e32 v69, v82
	v_mov_b32_e32 v70, v82
	v_mov_b32_e32 v71, v82
	v_mov_b32_e32 v72, v82
	v_mov_b32_e32 v73, v82
	v_mov_b32_e32 v74, v82
	v_mov_b32_e32 v75, v82
	v_mov_b32_e32 v76, v82
	v_mov_b32_e32 v77, v82
	v_mov_b32_e32 v78, v82
	v_mov_b32_e32 v79, v82
	v_mov_b32_e32 v80, v82
	v_mov_b32_e32 v81, v82
	s_branch .LSPs_sqk
